# s5_sample: wave reductions via DPP row ops + permlane16/32 swaps instead of ds_bpermute; select-before-cross-row-reduce
# speedup vs baseline: 1.0085x; 1.0085x over previous
.LBB0_247:
	s_waitcnt lgkmcnt(0)
	ds_read_b64 v[2:3], v222
	s_waitcnt lgkmcnt(0)
	s_ashr_i32 s0, s0, 6
	v_readfirstlane_b32 s18, v3
	v_readfirstlane_b32 s19, v2
	ds_read_b64 v[2:3], v230
	s_waitcnt lgkmcnt(0)
	s_lshl_b32 s1, s1, 3
	v_readfirstlane_b32 s20, v3
	v_readfirstlane_b32 s21, v2
	ds_read_b64 v[2:3], v223
	s_waitcnt lgkmcnt(0)
	s_add_i32 s53, s1, s0
	v_readfirstlane_b32 s3, v3
	v_readfirstlane_b32 s2, v2
	ds_read_b64 v[2:3], v224
	s_waitcnt lgkmcnt(0)
	s_cmpk_gt_i32 s53, 0x1fff
	v_readfirstlane_b32 s27, v2
	v_mov_b32_e32 v2, 0x20050
	v_readfirstlane_b32 s25, v3
	ds_read_b64 v[2:3], v2
	s_waitcnt lgkmcnt(0)
	s_nop 0
	v_readfirstlane_b32 s16, v2
	v_mov_b32_e32 v2, 0x20040
	v_readfirstlane_b32 s17, v3
	ds_read_b64 v[2:3], v2
	s_waitcnt lgkmcnt(0)
	s_nop 0
	v_readfirstlane_b32 s12, v2
	v_mov_b32_e32 v2, 0x20048
	v_readfirstlane_b32 s13, v3
	ds_read_b64 v[2:3], v2
	s_waitcnt lgkmcnt(0)
	s_nop 0
	v_readfirstlane_b32 s14, v2
	v_mov_b32_e32 v2, 0x20058
	v_readfirstlane_b32 s15, v3
	ds_read_b64 v[2:3], v2
	s_waitcnt lgkmcnt(0)
	s_nop 0
	v_readfirstlane_b32 s0, v2
	v_mov_b32_e32 v2, 0x20060
	v_readfirstlane_b32 s1, v3
	ds_read_b64 v[2:3], v2
	s_waitcnt lgkmcnt(0)
	s_nop 0
	v_readfirstlane_b32 s10, v2
	v_mov_b32_e32 v2, 0x20010
	v_readfirstlane_b32 s11, v3
	ds_read_b64 v[2:3], v2
	s_waitcnt lgkmcnt(0)
	s_nop 0
	v_readfirstlane_b32 s66, v2
	v_mov_b32_e32 v2, 0x20018
	v_readfirstlane_b32 s67, v3
	ds_read_b64 v[2:3], v2
	s_waitcnt lgkmcnt(0)
	s_nop 0
	v_readfirstlane_b32 s68, v2
	v_mov_b32_e32 v2, 0x20068
	v_readfirstlane_b32 s69, v3
	ds_read_b64 v[2:3], v2
	s_waitcnt lgkmcnt(0)
	s_nop 0
	v_readfirstlane_b32 s6, v2
	v_mov_b32_e32 v2, 0x20070
	v_readfirstlane_b32 s7, v3
	ds_read_b64 v[2:3], v2
	s_waitcnt lgkmcnt(0)
	s_nop 0
	v_readfirstlane_b32 s9, v3
	v_readfirstlane_b32 s8, v2
	ds_read_b64 v[2:3], v230
	s_waitcnt lgkmcnt(0)
	s_nop 0
	v_readfirstlane_b32 s22, v3
	v_readfirstlane_b32 s23, v2
	s_cbranch_scc1 .LBB0_265
	s_lshl_b64 s[4:5], s[40:41], 2
	s_add_u32 s2, s2, s4
	s_addc_u32 s3, s3, s5
	s_and_b32 s24, s53, 63
	v_and_b32_e32 v34, 63, v35
	v_and_b32_e32 v145, 15, v35
	s_or_b32 s26, s24, s26
	v_lshl_or_b32 v154, s26, 6, v34
	v_lshlrev_b64 v[2:3], 2, v[154:155]
	v_lshl_add_u64 v[4:5], s[16:17], 0, v[2:3]
	global_load_dword v36, v[4:5], off
	v_lshl_add_u64 v[4:5], s[14:15], 0, v[2:3]
	global_load_dword v40, v[4:5], off
	v_lshl_add_u64 v[2:3], s[12:13], 0, v[2:3]
	global_load_dword v41, v[2:3], off
	v_lshlrev_b64 v[2:3], 6, v[154:155]
	v_lshl_add_u64 v[4:5], s[0:1], 0, v[2:3]
	s_waitcnt vmcnt(7)
	v_lshl_add_u64 v[6:7], s[10:11], 0, v[2:3]
	global_load_dwordx4 v[26:29], v[6:7], off
	global_load_dwordx4 v[30:33], v[4:5], off
	global_load_dwordx4 v[10:13], v[6:7], off offset:16
	global_load_dwordx4 v[14:17], v[4:5], off offset:16
	global_load_dwordx4 v[18:21], v[4:5], off offset:48
	s_nop 0
	global_load_dwordx4 v[2:5], v[4:5], off offset:32
	s_nop 0
	global_load_dwordx4 v[22:25], v[6:7], off offset:48
	s_nop 0
	global_load_dwordx4 v[6:9], v[6:7], off offset:32
	s_mov_b32 s10, 0x3fb8aa3b
	v_mov_b32_e32 v50, 0x7f800000
	v_lshl_or_b32 v154, s26, 10, v34
	v_cmp_eq_u32_e64 s[12:13], 12, v145
	v_cmp_eq_u32_e64 s[14:15], 11, v145
	v_cmp_eq_u32_e64 s[16:17], 10, v145
	v_cmp_eq_u32_e64 s[28:29], 4, v145
	v_cmp_eq_u32_e64 s[30:31], 3, v145
	v_cmp_eq_u32_e64 s[34:35], 2, v145
	v_cmp_eq_u32_e64 s[36:37], 1, v145
	v_cmp_eq_u32_e64 s[38:39], 0, v145
	s_waitcnt vmcnt(10)
	v_mul_f32_e32 v37, 0x3fb8aa3b, v36
	v_fma_f32 v38, v36, s10, -v37
	s_waitcnt vmcnt(9)
	v_mul_f32_e32 v42, v40, v40
	v_rndne_f32_e32 v39, v37
	s_waitcnt vmcnt(8)
	v_fmac_f32_e32 v42, v41, v41
	v_fmac_f32_e32 v38, 0x32a5705f, v36
	v_sub_f32_e32 v37, v37, v39
	v_div_scale_f32 v43, s[0:1], v42, v42, 1.0
	v_add_f32_e32 v37, v37, v38
	v_cvt_i32_f32_e32 v39, v39
	v_rcp_f32_e32 v44, v43
	v_exp_f32_e32 v37, v37
	v_cmp_ngt_f32_e64 s[0:1], s87, v36
	v_div_scale_f32 v38, vcc, 1.0, v42, 1.0
	v_fma_f32 v45, -v43, v44, 1.0
	v_ldexp_f32 v37, v37, v39
	v_fmac_f32_e32 v44, v45, v44
	v_cndmask_b32_e64 v37, 0, v37, s[0:1]
	v_cmp_nlt_f32_e64 s[0:1], s93, v36
	v_mul_f32_e32 v45, v38, v44
	s_nop 0
	v_cndmask_b32_e64 v36, v50, v37, s[0:1]
	v_fma_f32 v37, -v43, v45, v38
	v_mul_f32_e32 v46, v41, v36
	v_mul_f32_e32 v36, v36, v40
	v_fmac_f32_e32 v45, v37, v44
	v_mul_f32_e32 v47, 0x3fb8aa3b, v46
	s_mov_b32 s0, 0x6dc9c883
	v_cvt_f64_f32_e32 v[36:37], v36
	v_fma_f32 v43, -v43, v45, v38
	v_fma_f32 v48, v46, s10, -v47
	v_rndne_f32_e32 v49, v47
	s_mov_b32 s1, 0x3fc45f30
	v_mul_f64 v[38:39], v[36:37], s[0:1]
	v_div_fmas_f32 v43, v43, v44, v45
	v_fmac_f32_e32 v48, 0x32a5705f, v46
	v_sub_f32_e32 v44, v47, v49
	v_floor_f64_e32 v[38:39], v[38:39]
	v_div_fixup_f32 v42, v43, v42, 1.0
	v_add_f32_e32 v43, v44, v48
	v_cvt_i32_f32_e32 v45, v49
	v_fma_f64 v[36:37], v[36:37], s[0:1], -v[38:39]
	v_exp_f32_e32 v38, v43
	v_cvt_f32_f64_e32 v36, v[36:37]
	v_sin_f32_e32 v37, v36
	v_cos_f32_e32 v36, v36
	v_ldexp_f32 v38, v38, v45
	v_cmp_ngt_f32_e32 vcc, s87, v46
	v_cmp_eq_u32_e64 s[10:11], 13, v145
	s_nop 0
	v_cndmask_b32_e32 v38, 0, v38, vcc
	v_cmp_nlt_f32_e32 vcc, s93, v46
	s_nop 1
	v_cndmask_b32_e32 v38, v50, v38, vcc
	v_mul_f32_e32 v156, v38, v36
	v_fma_f32 v36, v38, v36, -1.0
	v_mul_f32_e32 v157, v38, v37
	v_mul_f32_e32 v37, v41, v36
	v_mul_f32_e32 v36, v40, v36
	v_fmac_f32_e32 v37, v40, v157
	v_fma_f32 v38, v41, v157, -v36
	v_mul_f32_e32 v36, v42, v37
	v_mul_f32_e32 v37, v42, v38
	s_waitcnt vmcnt(4)
	v_mul_f32_e32 v162, v14, v37
	v_mul_f32_e32 v42, v10, v37
	v_fmac_f32_e32 v162, v10, v36
	s_waitcnt vmcnt(0)
	v_mul_f32_e32 v10, v6, v37
	v_fma_f32 v174, v2, v36, -v10
	v_mul_f32_e32 v175, v2, v37
	v_mul_f32_e32 v2, v7, v37
	v_fma_f32 v176, v3, v36, -v2
	v_mul_f32_e32 v2, v8, v37
	v_fma_f32 v178, v4, v36, -v2
	v_mul_f32_e32 v2, v9, v37
	v_mul_f32_e32 v158, v30, v37
	v_mul_f32_e32 v159, v31, v37
	v_mul_f32_e32 v177, v3, v37
	v_fma_f32 v180, v5, v36, -v2
	v_lshlrev_b64 v[2:3], 2, v[154:155]
	v_mul_f32_e32 v38, v26, v37
	v_mul_f32_e32 v39, v27, v37
	v_fmac_f32_e32 v158, v26, v36
	v_fmac_f32_e32 v159, v27, v36
	v_lshl_add_u64 v[26:27], s[6:7], 0, v[2:3]
	s_lshl_b32 s6, s24, 6
	v_mul_f32_e32 v160, v32, v37
	v_mul_f32_e32 v161, v33, v37
	v_mul_f32_e32 v43, v11, v37
	v_mul_f32_e32 v163, v15, v37
	v_mul_f32_e32 v44, v12, v37
	v_mul_f32_e32 v164, v16, v37
	v_mul_f32_e32 v45, v13, v37
	v_mul_f32_e32 v165, v17, v37
	v_fma_f32 v170, v14, v36, -v42
	v_mul_f32_e32 v179, v4, v37
	v_mul_f32_e32 v181, v5, v37
	v_mov_b32_e32 v14, s6
	v_mul_f32_e32 v40, v28, v37
	v_mul_f32_e32 v41, v29, v37
	v_fmac_f32_e32 v160, v28, v36
	v_fmac_f32_e32 v161, v29, v36
	v_fma_f32 v171, v15, v36, -v43
	v_fmac_f32_e32 v163, v11, v36
	v_fma_f32 v172, v16, v36, -v44
	v_fmac_f32_e32 v164, v12, v36
	v_fma_f32 v173, v17, v36, -v45
	v_fmac_f32_e32 v165, v13, v36
	v_fmac_f32_e32 v175, v6, v36
	v_fmac_f32_e32 v177, v7, v36
	v_fmac_f32_e32 v179, v8, v36
	v_fmac_f32_e32 v181, v9, v36
	v_lshl_add_u64 v[28:29], s[8:9], 0, v[2:3]
	global_load_dwordx4 v[2:5], v14, s[2:3]
	global_load_dwordx4 v[6:9], v14, s[2:3] offset:16
	global_load_dwordx4 v[10:13], v14, s[2:3] offset:32
	s_nop 0
	global_load_dwordx4 v[14:17], v14, s[2:3] offset:48
	s_nop 0
	global_load_dword v182, v[26:27], off
	global_load_dword v183, v[26:27], off offset:256
	global_load_dword v184, v[26:27], off offset:512
	global_load_dword v185, v[26:27], off offset:768
	global_load_dword v186, v[26:27], off offset:1024
	global_load_dword v187, v[26:27], off offset:1280
	global_load_dword v188, v[26:27], off offset:1536
	global_load_dword v189, v[26:27], off offset:1792
	global_load_dword v190, v[28:29], off
	global_load_dword v191, v[28:29], off offset:256
	global_load_dword v192, v[28:29], off offset:512
	global_load_dword v193, v[28:29], off offset:768
	global_load_dword v194, v[28:29], off offset:1024
	global_load_dword v195, v[28:29], off offset:1280
	global_load_dword v196, v[28:29], off offset:1536
	global_load_dword v197, v[28:29], off offset:1792
	global_load_dword v198, v[26:27], off offset:2048
	global_load_dword v199, v[26:27], off offset:2304
	global_load_dword v200, v[26:27], off offset:2560
	global_load_dword v201, v[26:27], off offset:2816
	global_load_dword v202, v[26:27], off offset:3072
	global_load_dword v203, v[26:27], off offset:3328
	global_load_dword v204, v[26:27], off offset:3584
	global_load_dword v205, v[26:27], off offset:3840
	global_load_dword v206, v[28:29], off offset:2048
	global_load_dword v207, v[28:29], off offset:2304
	global_load_dword v208, v[28:29], off offset:2560
	global_load_dword v209, v[28:29], off offset:2816
	global_load_dword v210, v[28:29], off offset:3072
	global_load_dword v211, v[28:29], off offset:3328
	global_load_dword v212, v[28:29], off offset:3584
	global_load_dword v213, v[28:29], off offset:3840
	v_lshlrev_b32_e32 v26, 2, v35
	v_and_b32_e32 v26, 60, v26
	s_add_u32 s0, s27, s4
	v_or_b32_e32 v27, s6, v26
	s_addc_u32 s1, s25, s5
	global_load_dword v214, v27, s[2:3]
	global_load_dword v215, v27, s[0:1]
	v_fma_f32 v166, v30, v36, -v38
	v_mul_f32_e32 v30, v22, v37
	v_fma_f32 v216, v18, v36, -v30
	v_mul_f32_e32 v217, v18, v37
	v_mul_f32_e32 v18, v23, v37
	v_fma_f32 v218, v19, v36, -v18
	v_mul_f32_e32 v18, v24, v37
	s_lshl_b32 s40, s51, 7
	v_fma_f32 v220, v20, v36, -v18
	v_mul_f32_e32 v18, v25, v37
	s_add_u32 s0, s21, 0x4000000
	v_mul_f32_e32 v219, v19, v37
	v_fma_f32 v234, v21, v36, -v18
	s_addc_u32 s1, s20, 0
	v_lshlrev_b32_e32 v18, 4, v34
	v_mov_b32_e32 v19, v155
	v_lshl_add_u64 v[146:147], s[0:1], 0, v[18:19]
	s_add_u32 s0, s0, s6
	s_addc_u32 s1, s1, 0
	s_lshl_b32 s2, s24, 8
	s_add_u32 s2, s23, s2
	v_lshlrev_b32_e32 v154, 2, v34
	s_addc_u32 s3, s22, 0
	v_lshl_add_u64 v[150:151], s[2:3], 0, v[154:155]
	s_add_u32 s2, s19, s6
	s_addc_u32 s3, s18, 0
	v_mul_f32_e32 v221, v20, v37
	v_mul_f32_e32 v235, v21, v37
	v_lshl_add_u64 v[20:21], s[2:3], 0, v[154:155]
	v_and_b32_e32 v19, 64, v1
	v_lshl_add_u64 v[152:153], v[20:21], 0, s[60:61]
	v_add_u32_e32 v19, 64, v19
	v_xor_b32_e32 v20, 1, v1
	v_cmp_lt_i32_e32 vcc, v20, v19
	v_mov_b32_e32 v27, v155
	v_or_b32_e32 v18, s6, v34
	v_cndmask_b32_e32 v20, v1, v20, vcc
	v_lshlrev_b32_e32 v154, 2, v20
	v_xor_b32_e32 v20, 2, v1
	v_cmp_lt_i32_e32 vcc, v20, v19
	v_fma_f32 v167, v31, v36, -v39
	v_fma_f32 v168, v32, v36, -v40
	v_cndmask_b32_e32 v20, v1, v20, vcc
	v_lshlrev_b32_e32 v236, 2, v20
	v_xor_b32_e32 v20, 4, v1
	v_cmp_lt_i32_e32 vcc, v20, v19
	v_fma_f32 v169, v33, v36, -v41
	v_fmac_f32_e32 v217, v22, v36
	v_cndmask_b32_e32 v20, v1, v20, vcc
	v_lshlrev_b32_e32 v237, 2, v20
	v_xor_b32_e32 v20, 8, v1
	v_cmp_lt_i32_e32 vcc, v20, v19
	v_fmac_f32_e32 v219, v23, v36
	v_fmac_f32_e32 v221, v24, v36
	v_cndmask_b32_e32 v20, v1, v20, vcc
	v_lshlrev_b32_e32 v238, 2, v20
	v_xor_b32_e32 v20, 16, v1
	v_cmp_lt_i32_e32 vcc, v20, v19
	v_fmac_f32_e32 v235, v25, v36
	v_lshl_add_u64 v[148:149], s[0:1], 0, v[26:27]
	v_cndmask_b32_e32 v20, v1, v20, vcc
	v_lshlrev_b32_e32 v239, 2, v20
	v_xor_b32_e32 v20, 32, v1
	v_cmp_lt_i32_e32 vcc, v20, v19
	v_cmp_gt_u32_e64 s[4:5], 16, v34
	v_cmp_eq_u32_e64 s[6:7], 15, v145
	v_cndmask_b32_e32 v19, v1, v20, vcc
	v_lshlrev_b32_e32 v240, 2, v19
	v_cmp_eq_u32_e64 s[8:9], 14, v145
	v_cmp_eq_u32_e64 s[18:19], 9, v145
	v_cmp_eq_u32_e64 s[20:21], 8, v145
	v_cmp_eq_u32_e64 s[22:23], 7, v145
	v_cmp_eq_u32_e64 s[24:25], 6, v145
	v_cmp_eq_u32_e64 s[26:27], 5, v145
	v_lshlrev_b32_e32 v241, 2, v18
	s_branch .LBB0_251

.LBB0_251:
	s_ashr_i32 s82, s53, 6
	s_ashr_i32 s83, s82, 31
	s_add_i32 s3, s52, s53
	s_lshl_b64 s[78:79], s[82:83], 12
	s_ashr_i32 s2, s3, 6
	s_cmpk_lt_i32 s3, 0x2000
	s_cselect_b64 s[80:81], -1, 0
	s_and_b64 s[70:71], s[80:81], exec
	s_cselect_b32 s70, s2, 0
	s_ashr_i32 s71, s70, 31
	s_lshl_b64 s[72:73], s[70:71], 12
	s_add_u32 s74, s0, s72
	s_waitcnt lgkmcnt(14)
	v_lshl_add_u64 v[18:19], v[148:149], 0, s[78:79]
	s_addc_u32 s75, s1, s73
	s_add_i32 s70, s70, s40
	global_load_dword v250, v[18:19], off
	v_lshl_add_u64 v[18:19], v[146:147], 0, s[72:73]
	s_ashr_i32 s71, s70, 31
	s_add_i32 s3, s52, s3
	s_waitcnt lgkmcnt(2)
	global_load_dwordx4 v[110:113], v[18:19], off
	global_load_dwordx4 v[106:109], v[18:19], off offset:1024
	global_load_dwordx4 v[98:101], v[18:19], off offset:2048
	global_load_dwordx4 v[102:105], v[18:19], off offset:3072
	v_lshl_add_u64 v[18:19], v[148:149], 0, s[72:73]
	s_lshl_b64 s[70:71], s[70:71], 14
	s_ashr_i32 s72, s3, 6
	s_cmpk_lt_i32 s3, 0x2000
	s_cselect_b64 s[76:77], -1, 0
	s_waitcnt lgkmcnt(1)
	global_load_dwordx4 v[82:85], v155, s[74:75] offset:48
	s_waitcnt lgkmcnt(0)
	global_load_dwordx4 v[86:89], v155, s[74:75] offset:32
	global_load_dwordx4 v[90:93], v155, s[74:75] offset:16
	global_load_dwordx4 v[94:97], v155, s[74:75]
	global_load_dword v247, v[18:19], off
	v_or_b32_e32 v18, s70, v241
	v_mov_b32_e32 v19, s71
	s_and_b64 s[70:71], s[76:77], exec
	s_cselect_b32 s70, s72, 0
	s_ashr_i32 s71, s70, 31
	s_lshl_b64 s[74:75], s[70:71], 12
	s_add_u32 vcc_lo, s0, s74
	v_lshl_add_u64 v[20:21], s[66:67], 0, v[18:19]
	v_lshl_add_u64 v[18:19], s[68:69], 0, v[18:19]
	s_addc_u32 vcc_hi, s1, s75
	s_add_i32 s70, s70, s40
	global_load_dword v249, v[18:19], off
	v_lshl_add_u64 v[18:19], v[146:147], 0, s[74:75]
	s_ashr_i32 s71, s70, 31
	global_load_dword v248, v[20:21], off
	global_load_dwordx4 v[78:81], v[18:19], off
	global_load_dwordx4 v[74:77], v[18:19], off offset:1024
	global_load_dwordx4 v[66:69], v[18:19], off offset:2048
	global_load_dwordx4 v[70:73], v[18:19], off offset:3072
	v_lshl_add_u64 v[18:19], v[148:149], 0, s[74:75]
	s_lshl_b64 s[70:71], s[70:71], 14
	s_add_i32 s55, s52, s3
	global_load_dwordx4 v[50:53], v155, vcc offset:48
	global_load_dwordx4 v[54:57], v155, vcc offset:32
	global_load_dwordx4 v[58:61], v155, vcc offset:16
	global_load_dwordx4 v[62:65], v155, vcc
	global_load_dword v244, v[18:19], off
	v_or_b32_e32 v18, s70, v241
	s_ashr_i32 s70, s55, 6
	s_cmpk_lt_i32 s55, 0x2000
	s_cselect_b64 s[74:75], -1, 0
	s_and_b64 vcc, s[74:75], exec
	s_cselect_b32 vcc_lo, s70, 0
	s_ashr_i32 vcc_hi, vcc_lo, 31
	v_mov_b32_e32 v19, s71
	s_lshl_b64 s[94:95], vcc, 12
	v_lshl_add_u64 v[20:21], s[66:67], 0, v[18:19]
	v_lshl_add_u64 v[18:19], s[68:69], 0, v[18:19]
	s_add_u32 s56, s0, s94
	global_load_dword v246, v[18:19], off
	v_lshl_add_u64 v[18:19], v[146:147], 0, s[94:95]
	s_addc_u32 s57, s1, s95
	global_load_dword v245, v[20:21], off
	global_load_dwordx4 v[46:49], v[18:19], off
	global_load_dwordx4 v[42:45], v[18:19], off offset:1024
	global_load_dwordx4 v[34:37], v[18:19], off offset:2048
	global_load_dwordx4 v[38:41], v[18:19], off offset:3072
	s_nop 0
	global_load_dwordx4 v[18:21], v155, s[56:57] offset:48
	global_load_dwordx4 v[22:25], v155, s[56:57] offset:32
	global_load_dwordx4 v[26:29], v155, s[56:57] offset:16
	global_load_dwordx4 v[30:33], v155, s[56:57]
	s_add_i32 s56, vcc_lo, s40
	s_ashr_i32 s57, s56, 31
	v_lshl_add_u64 v[114:115], v[148:149], 0, s[94:95]
	s_lshl_b64 s[56:57], s[56:57], 14
	global_load_dword v242, v[114:115], off
	v_or_b32_e32 v114, s56, v241
	s_add_i32 s56, s82, s40
	v_mov_b32_e32 v115, s57
	s_ashr_i32 s57, s56, 31
	v_lshl_add_u64 v[116:117], s[66:67], 0, v[114:115]
	v_lshl_add_u64 v[114:115], s[68:69], 0, v[114:115]
	s_lshl_b64 s[82:83], s[56:57], 14
	global_load_dword v243, v[114:115], off
	v_or_b32_e32 v114, s82, v241
	v_mov_b32_e32 v115, s83
	s_add_u32 s56, s0, s78
	global_load_dword v228, v[116:117], off
	v_lshl_add_u64 v[116:117], s[68:69], 0, v[114:115]
	v_lshl_add_u64 v[114:115], s[66:67], 0, v[114:115]
	s_addc_u32 s57, s1, s79
	v_lshl_add_u64 v[142:143], v[146:147], 0, s[78:79]
	global_load_dword v251, v[116:117], off
	global_load_dword v252, v[114:115], off
	s_nop 0
	global_load_dwordx4 v[114:117], v155, s[56:57] offset:48
	global_load_dwordx4 v[118:121], v155, s[56:57] offset:32
	global_load_dwordx4 v[122:125], v155, s[56:57] offset:16
	global_load_dwordx4 v[126:129], v155, s[56:57]
	global_load_dwordx4 v[130:133], v[142:143], off offset:3072
	global_load_dwordx4 v[134:137], v[142:143], off offset:2048
	global_load_dwordx4 v[138:141], v[142:143], off offset:1024
	s_nop 0
	global_load_dwordx4 v[142:145], v[142:143], off
	s_waitcnt vmcnt(1)
	v_pk_mul_f32 v[140:141], v[140:141], v[140:141]
	s_waitcnt vmcnt(0)
	v_pk_mul_f32 v[144:145], v[144:145], v[144:145]
	v_pk_mul_f32 v[142:143], v[142:143], v[142:143]
	v_pk_mul_f32 v[138:139], v[138:139], v[138:139]
	v_pk_mov_b32 v[232:233], v[142:143], v[144:145] op_sel:[1,0]
	v_mov_b32_e32 v143, v145
	v_pk_mov_b32 v[144:145], v[138:139], v[140:141] op_sel:[1,0]
	v_mov_b32_e32 v139, v141
	v_pk_add_f32 v[138:139], v[144:145], v[138:139]
	v_pk_add_f32 v[142:143], v[232:233], v[142:143]
	v_pk_add_f32 v[138:139], v[138:139], v[138:139] op_sel_hi:[0,1]
	v_mul_f32_e32 v138, v134, v134
	v_pk_fma_f32 v[134:135], v[134:135], v[134:135], v[138:139] op_sel_hi:[1,1,0]
	v_pk_add_f32 v[142:143], v[142:143], v[142:143] op_sel_hi:[0,1]
	v_mul_f32_e32 v134, v136, v136
	v_pk_fma_f32 v[136:137], v[136:137], v[136:137], v[134:135] op_sel_hi:[1,1,0]
	v_mul_f32_e32 v134, v130, v130
	v_mul_f32_e32 v136, v131, v131
	v_mul_f32_e32 v138, v132, v132
	v_mul_f32_e32 v142, v133, v133
	v_pk_add_f32 v[130:131], v[134:135], v[136:137]
	v_pk_add_f32 v[132:133], v[138:139], v[142:143]
	s_nop 0
	v_pk_add_f32 v[130:131], v[130:131], v[132:133]
	s_nop 0
	v_add_f32_e32 v130, v130, v131
	s_nop 1
	v_add_f32_dpp v130, v130, v130 quad_perm:[1,0,3,2] row_mask:0xf bank_mask:0xf
	s_nop 1
	v_add_f32_dpp v130, v130, v130 quad_perm:[2,3,0,1] row_mask:0xf bank_mask:0xf
	s_nop 1
	v_add_f32_dpp v130, v130, v130 row_half_mirror row_mask:0xf bank_mask:0xf
	s_nop 1
	v_add_f32_dpp v130, v130, v130 row_mirror row_mask:0xf bank_mask:0xf
	v_mov_b32_e32 v131, v130
	s_nop 1
	v_permlane16_swap_b32 v131, v130
	v_add_f32_e32 v130, v130, v131
	v_mov_b32_e32 v131, v130
	s_nop 1
	v_permlane32_swap_b32 v131, v130
	v_add_f32_e32 v130, v130, v131
	v_fmamk_f32 v130, v130, 0x3a800000, v225
	v_cmp_gt_f32_e32 vcc, s90, v130
	v_mul_f32_e32 v131, 0x4b800000, v130
	s_nop 0
	v_cndmask_b32_e32 v130, v130, v131, vcc
	v_rsq_f32_e32 v130, v130
	s_nop 0
	v_mul_f32_e32 v131, 0x45800000, v130
	v_cndmask_b32_e32 v130, v130, v131, vcc
	v_mul_f32_e32 v126, v126, v130
	v_mul_f32_e32 v126, v2, v126
	v_mul_f32_e32 v127, v127, v130
	v_fma_f32 v131, v166, v126, 0
	v_fma_f32 v126, v158, v126, 0
	v_mul_f32_e32 v127, v3, v127
	v_fmac_f32_e32 v131, v167, v127
	v_fmac_f32_e32 v126, v159, v127
	v_mul_f32_e32 v127, v128, v130
	v_mul_f32_e32 v127, v4, v127
	v_fmac_f32_e32 v131, v168, v127
	v_fmac_f32_e32 v126, v160, v127
	v_mul_f32_e32 v127, v129, v130
	v_mul_f32_e32 v127, v5, v127
	v_mul_f32_e32 v122, v122, v130
	v_fmac_f32_e32 v131, v169, v127
	v_fmac_f32_e32 v126, v161, v127
	v_mul_f32_e32 v122, v6, v122
	v_fmac_f32_e32 v131, v170, v122
	v_fmac_f32_e32 v126, v162, v122
	v_mul_f32_e32 v122, v123, v130
	v_mul_f32_e32 v122, v7, v122
	v_fmac_f32_e32 v131, v171, v122
	v_fmac_f32_e32 v126, v163, v122
	v_mul_f32_e32 v122, v124, v130
	v_mul_f32_e32 v122, v8, v122
	v_fmac_f32_e32 v131, v172, v122
	v_fmac_f32_e32 v126, v164, v122
	v_mul_f32_e32 v122, v125, v130
	v_mul_f32_e32 v122, v9, v122
	v_mul_f32_e32 v118, v118, v130
	v_fmac_f32_e32 v131, v173, v122
	v_fmac_f32_e32 v126, v165, v122
	v_mul_f32_e32 v118, v10, v118
	v_fmac_f32_e32 v131, v174, v118
	v_fmac_f32_e32 v126, v175, v118
	v_mul_f32_e32 v118, v119, v130
	v_mul_f32_e32 v118, v11, v118
	v_fmac_f32_e32 v131, v176, v118
	v_fmac_f32_e32 v126, v177, v118
	v_mul_f32_e32 v118, v120, v130
	v_mul_f32_e32 v118, v12, v118
	v_fmac_f32_e32 v131, v178, v118
	v_fmac_f32_e32 v126, v179, v118
	v_mul_f32_e32 v118, v121, v130
	v_mul_f32_e32 v118, v13, v118
	v_mul_f32_e32 v114, v114, v130
	v_fmac_f32_e32 v131, v180, v118
	v_fmac_f32_e32 v126, v181, v118
	v_mul_f32_e32 v114, v14, v114
	v_fmac_f32_e32 v131, v216, v114
	v_fmac_f32_e32 v126, v217, v114
	v_mul_f32_e32 v114, v115, v130
	v_mul_f32_e32 v114, v15, v114
	v_fmac_f32_e32 v131, v218, v114
	v_fmac_f32_e32 v126, v219, v114
	v_mul_f32_e32 v114, v116, v130
	v_mul_f32_e32 v114, v16, v114
	v_fmac_f32_e32 v131, v220, v114
	v_fmac_f32_e32 v126, v221, v114
	v_mul_f32_e32 v114, v117, v130
	v_lshl_add_u64 v[116:117], v[150:151], 0, s[82:83]
	v_mul_f32_e32 v114, v17, v114
	v_add_co_u32_e32 v118, vcc, s97, v116
	v_fmac_f32_e32 v131, v234, v114
	v_fmac_f32_e32 v126, v235, v114
	v_mul_f32_e32 v114, v157, v251
	v_mul_f32_e32 v115, v157, v252
	v_addc_co_u32_e32 v119, vcc, 0, v117, vcc
	v_fma_f32 v114, v156, v252, -v114
	v_fmac_f32_e32 v115, v156, v251
	v_add_co_u32_e32 v116, vcc, s88, v116
	v_add_f32_e32 v114, v114, v131
	v_add_f32_e32 v115, v115, v126
	v_addc_co_u32_e32 v117, vcc, 0, v117, vcc
	global_store_dword v[118:119], v114, off
	global_store_dword v[116:117], v115, off
	v_mul_f32_e32 v116, v190, v115
	v_mul_f32_e32 v118, v191, v115
	v_mul_f32_e32 v120, v192, v115
	v_mul_f32_e32 v122, v193, v115
	v_mul_f32_e32 v124, v194, v115
	v_mul_f32_e32 v126, v195, v115
	v_mul_f32_e32 v128, v196, v115
	v_mul_f32_e32 v131, v197, v115
	v_mul_f32_e32 v133, v206, v115
	v_mul_f32_e32 v135, v207, v115
	v_mul_f32_e32 v137, v208, v115
	v_mul_f32_e32 v139, v209, v115
	v_mul_f32_e32 v141, v210, v115
	v_mul_f32_e32 v143, v211, v115
	v_mul_f32_e32 v145, v212, v115
	v_mul_f32_e32 v115, v213, v115
	v_fma_f32 v116, v182, v114, -v116
	v_fma_f32 v118, v183, v114, -v118
	v_fma_f32 v120, v184, v114, -v120
	v_fma_f32 v122, v185, v114, -v122
	v_fma_f32 v124, v186, v114, -v124
	v_fma_f32 v126, v187, v114, -v126
	v_fma_f32 v128, v188, v114, -v128
	v_fma_f32 v131, v189, v114, -v131
	v_fma_f32 v133, v198, v114, -v133
	v_fma_f32 v135, v199, v114, -v135
	v_fma_f32 v137, v200, v114, -v137
	v_fma_f32 v139, v201, v114, -v139
	v_fma_f32 v141, v202, v114, -v141
	v_fma_f32 v143, v203, v114, -v143
	v_fma_f32 v145, v204, v114, -v145
	v_fma_f32 v114, v205, v114, -v115
	v_add_f32_dpp v116, v116, v116 quad_perm:[1,0,3,2] row_mask:0xf bank_mask:0xf
	v_add_f32_dpp v118, v118, v118 quad_perm:[1,0,3,2] row_mask:0xf bank_mask:0xf
	v_add_f32_dpp v120, v120, v120 quad_perm:[1,0,3,2] row_mask:0xf bank_mask:0xf
	v_add_f32_dpp v122, v122, v122 quad_perm:[1,0,3,2] row_mask:0xf bank_mask:0xf
	v_add_f32_dpp v124, v124, v124 quad_perm:[1,0,3,2] row_mask:0xf bank_mask:0xf
	v_add_f32_dpp v126, v126, v126 quad_perm:[1,0,3,2] row_mask:0xf bank_mask:0xf
	v_add_f32_dpp v128, v128, v128 quad_perm:[1,0,3,2] row_mask:0xf bank_mask:0xf
	v_add_f32_dpp v131, v131, v131 quad_perm:[1,0,3,2] row_mask:0xf bank_mask:0xf
	v_add_f32_dpp v133, v133, v133 quad_perm:[1,0,3,2] row_mask:0xf bank_mask:0xf
	v_add_f32_dpp v135, v135, v135 quad_perm:[1,0,3,2] row_mask:0xf bank_mask:0xf
	v_add_f32_dpp v137, v137, v137 quad_perm:[1,0,3,2] row_mask:0xf bank_mask:0xf
	v_add_f32_dpp v139, v139, v139 quad_perm:[1,0,3,2] row_mask:0xf bank_mask:0xf
	v_add_f32_dpp v141, v141, v141 quad_perm:[1,0,3,2] row_mask:0xf bank_mask:0xf
	v_add_f32_dpp v143, v143, v143 quad_perm:[1,0,3,2] row_mask:0xf bank_mask:0xf
	v_add_f32_dpp v145, v145, v145 quad_perm:[1,0,3,2] row_mask:0xf bank_mask:0xf
	s_nop 1
	v_add_f32_dpp v114, v114, v114 quad_perm:[1,0,3,2] row_mask:0xf bank_mask:0xf
	v_add_f32_dpp v116, v116, v116 quad_perm:[2,3,0,1] row_mask:0xf bank_mask:0xf
	v_add_f32_dpp v118, v118, v118 quad_perm:[2,3,0,1] row_mask:0xf bank_mask:0xf
	v_add_f32_dpp v120, v120, v120 quad_perm:[2,3,0,1] row_mask:0xf bank_mask:0xf
	v_add_f32_dpp v122, v122, v122 quad_perm:[2,3,0,1] row_mask:0xf bank_mask:0xf
	v_add_f32_dpp v124, v124, v124 quad_perm:[2,3,0,1] row_mask:0xf bank_mask:0xf
	v_add_f32_dpp v126, v126, v126 quad_perm:[2,3,0,1] row_mask:0xf bank_mask:0xf
	v_add_f32_dpp v128, v128, v128 quad_perm:[2,3,0,1] row_mask:0xf bank_mask:0xf
	v_add_f32_dpp v131, v131, v131 quad_perm:[2,3,0,1] row_mask:0xf bank_mask:0xf
	v_add_f32_dpp v133, v133, v133 quad_perm:[2,3,0,1] row_mask:0xf bank_mask:0xf
	v_add_f32_dpp v135, v135, v135 quad_perm:[2,3,0,1] row_mask:0xf bank_mask:0xf
	v_add_f32_dpp v137, v137, v137 quad_perm:[2,3,0,1] row_mask:0xf bank_mask:0xf
	v_add_f32_dpp v139, v139, v139 quad_perm:[2,3,0,1] row_mask:0xf bank_mask:0xf
	v_add_f32_dpp v141, v141, v141 quad_perm:[2,3,0,1] row_mask:0xf bank_mask:0xf
	v_add_f32_dpp v143, v143, v143 quad_perm:[2,3,0,1] row_mask:0xf bank_mask:0xf
	v_add_f32_dpp v145, v145, v145 quad_perm:[2,3,0,1] row_mask:0xf bank_mask:0xf
	s_nop 1
	v_add_f32_dpp v114, v114, v114 quad_perm:[2,3,0,1] row_mask:0xf bank_mask:0xf
	v_add_f32_dpp v116, v116, v116 row_half_mirror row_mask:0xf bank_mask:0xf
	v_add_f32_dpp v118, v118, v118 row_half_mirror row_mask:0xf bank_mask:0xf
	v_add_f32_dpp v120, v120, v120 row_half_mirror row_mask:0xf bank_mask:0xf
	v_add_f32_dpp v122, v122, v122 row_half_mirror row_mask:0xf bank_mask:0xf
	v_add_f32_dpp v124, v124, v124 row_half_mirror row_mask:0xf bank_mask:0xf
	v_add_f32_dpp v126, v126, v126 row_half_mirror row_mask:0xf bank_mask:0xf
	v_add_f32_dpp v128, v128, v128 row_half_mirror row_mask:0xf bank_mask:0xf
	v_add_f32_dpp v131, v131, v131 row_half_mirror row_mask:0xf bank_mask:0xf
	v_add_f32_dpp v133, v133, v133 row_half_mirror row_mask:0xf bank_mask:0xf
	v_add_f32_dpp v135, v135, v135 row_half_mirror row_mask:0xf bank_mask:0xf
	v_add_f32_dpp v137, v137, v137 row_half_mirror row_mask:0xf bank_mask:0xf
	v_add_f32_dpp v139, v139, v139 row_half_mirror row_mask:0xf bank_mask:0xf
	v_add_f32_dpp v141, v141, v141 row_half_mirror row_mask:0xf bank_mask:0xf
	v_add_f32_dpp v143, v143, v143 row_half_mirror row_mask:0xf bank_mask:0xf
	v_add_f32_dpp v145, v145, v145 row_half_mirror row_mask:0xf bank_mask:0xf
	s_nop 1
	v_add_f32_dpp v114, v114, v114 row_half_mirror row_mask:0xf bank_mask:0xf
	v_add_f32_dpp v116, v116, v116 row_mirror row_mask:0xf bank_mask:0xf
	v_add_f32_dpp v118, v118, v118 row_mirror row_mask:0xf bank_mask:0xf
	v_add_f32_dpp v120, v120, v120 row_mirror row_mask:0xf bank_mask:0xf
	v_add_f32_dpp v122, v122, v122 row_mirror row_mask:0xf bank_mask:0xf
	v_add_f32_dpp v124, v124, v124 row_mirror row_mask:0xf bank_mask:0xf
	v_add_f32_dpp v126, v126, v126 row_mirror row_mask:0xf bank_mask:0xf
	v_add_f32_dpp v128, v128, v128 row_mirror row_mask:0xf bank_mask:0xf
	v_add_f32_dpp v131, v131, v131 row_mirror row_mask:0xf bank_mask:0xf
	v_add_f32_dpp v133, v133, v133 row_mirror row_mask:0xf bank_mask:0xf
	v_add_f32_dpp v135, v135, v135 row_mirror row_mask:0xf bank_mask:0xf
	v_add_f32_dpp v137, v137, v137 row_mirror row_mask:0xf bank_mask:0xf
	v_add_f32_dpp v139, v139, v139 row_mirror row_mask:0xf bank_mask:0xf
	v_add_f32_dpp v141, v141, v141 row_mirror row_mask:0xf bank_mask:0xf
	v_add_f32_dpp v143, v143, v143 row_mirror row_mask:0xf bank_mask:0xf
	v_add_f32_dpp v145, v145, v145 row_mirror row_mask:0xf bank_mask:0xf
	s_nop 1
	v_add_f32_dpp v114, v114, v114 row_mirror row_mask:0xf bank_mask:0xf
	s_nop 1
	v_cndmask_b32_e64 v116, 0, v116, s[38:39]
	v_cndmask_b32_e64 v116, v116, v118, s[36:37]
	v_cndmask_b32_e64 v116, v116, v120, s[34:35]
	v_cndmask_b32_e64 v116, v116, v122, s[30:31]
	v_cndmask_b32_e64 v116, v116, v124, s[28:29]
	v_cndmask_b32_e64 v116, v116, v126, s[26:27]
	v_cndmask_b32_e64 v116, v116, v128, s[24:25]
	v_cndmask_b32_e64 v116, v116, v131, s[22:23]
	v_cndmask_b32_e64 v116, v116, v133, s[20:21]
	v_cndmask_b32_e64 v116, v116, v135, s[18:19]
	v_cndmask_b32_e64 v116, v116, v137, s[16:17]
	v_cndmask_b32_e64 v116, v116, v139, s[14:15]
	v_cndmask_b32_e64 v116, v116, v141, s[12:13]
	v_cndmask_b32_e64 v116, v116, v143, s[10:11]
	v_cndmask_b32_e64 v115, v116, v145, s[8:9]
	v_cndmask_b32_e64 v114, v115, v114, s[6:7]
	v_mov_b32_e32 v117, v114
	s_nop 1
	v_permlane16_swap_b32 v117, v114
	v_add_f32_e32 v114, v114, v117
	v_mov_b32_e32 v117, v114
	s_nop 1
	v_permlane32_swap_b32 v117, v114
	v_add_f32_e32 v114, v114, v117
	s_and_saveexec_b64 s[82:83], s[4:5]
	s_cbranch_execnz .LBB0_255
	s_or_b64 exec, exec, s[82:83]
	s_andn2_b64 vcc, exec, s[80:81]
	s_cbranch_vccz .LBB0_256

.LBB0_255:
	v_mul_f32_e32 v115, v250, v130
	v_mul_f32_e32 v115, v214, v115
	v_fmac_f32_e32 v114, v215, v115
	v_mul_f32_e32 v115, 0x3d372713, v114
	v_mul_f32_e32 v115, v114, v115
	v_fma_f32 v115, v114, v115, v114
	v_mul_f32_e32 v115, 0xbfcc422a, v115
	v_mul_f32_e32 v115, 0x3fb8aa3b, v115
	v_exp_f32_e32 v115, v115
	s_nop 0
	v_add_f32_e32 v115, 1.0, v115
	v_rcp_f32_e32 v115, v115
	s_nop 0
	v_mul_f32_e32 v116, v114, v115
	v_lshl_add_u64 v[114:115], v[152:153], 0, s[78:79]
	global_store_dword v[114:115], v116, off
	s_or_b64 exec, exec, s[82:83]
	s_andn2_b64 vcc, exec, s[80:81]
	s_cbranch_vccnz .LBB0_253
.LBB0_256:
	v_pk_mul_f32 v[112:113], v[112:113], v[112:113]
	v_pk_mul_f32 v[110:111], v[110:111], v[110:111]
	v_pk_mul_f32 v[108:109], v[108:109], v[108:109]
	v_pk_mul_f32 v[106:107], v[106:107], v[106:107]
	s_waitcnt lgkmcnt(0)
	v_pk_mov_b32 v[114:115], v[110:111], v[112:113] op_sel:[1,0]
	v_mov_b32_e32 v111, v113
	v_pk_mov_b32 v[112:113], v[106:107], v[108:109] op_sel:[1,0]
	v_mov_b32_e32 v107, v109
	v_pk_add_f32 v[110:111], v[114:115], v[110:111]
	v_pk_add_f32 v[106:107], v[112:113], v[106:107]
	v_mul_f32_e32 v108, v102, v102
	v_mul_f32_e32 v109, v103, v103
	v_mul_f32_e32 v112, v104, v104
	v_mul_f32_e32 v113, v105, v105
	v_pk_add_f32 v[102:103], v[110:111], v[110:111] op_sel:[0,1] op_sel_hi:[1,0]
	v_pk_add_f32 v[104:105], v[106:107], v[106:107] op_sel:[0,1] op_sel_hi:[1,0]
	v_mov_b32_e32 v103, v108
	v_mov_b32_e32 v105, v109
	v_pk_add_f32 v[102:103], v[102:103], v[104:105]
	v_mul_f32_e32 v104, v99, v99
	v_pk_fma_f32 v[98:99], v[98:99], v[98:99], v[104:105] op_sel_hi:[1,1,0]
	v_mul_f32_e32 v104, v101, v101
	v_pk_fma_f32 v[100:101], v[100:101], v[100:101], v[104:105] op_sel_hi:[1,1,0]
	v_mov_b32_e32 v99, v112
	v_mov_b32_e32 v101, v113
	v_pk_add_f32 v[98:99], v[98:99], v[100:101]
	s_add_i32 s56, s2, s40
	v_pk_add_f32 v[98:99], v[102:103], v[98:99]
	s_ashr_i32 s57, s56, 31
	v_add_f32_e32 v98, v98, v99
	s_lshl_b64 s[56:57], s[56:57], 14
	s_nop 1
	v_add_f32_dpp v98, v98, v98 quad_perm:[1,0,3,2] row_mask:0xf bank_mask:0xf
	s_nop 1
	v_add_f32_dpp v98, v98, v98 quad_perm:[2,3,0,1] row_mask:0xf bank_mask:0xf
	s_nop 1
	v_add_f32_dpp v98, v98, v98 row_half_mirror row_mask:0xf bank_mask:0xf
	s_nop 1
	v_add_f32_dpp v98, v98, v98 row_mirror row_mask:0xf bank_mask:0xf
	v_mov_b32_e32 v99, v98
	s_nop 1
	v_permlane16_swap_b32 v99, v98
	v_add_f32_e32 v98, v98, v99
	v_mov_b32_e32 v99, v98
	s_nop 1
	v_permlane32_swap_b32 v99, v98
	v_add_f32_e32 v98, v98, v99
	v_fmamk_f32 v98, v98, 0x3a800000, v225
	v_cmp_gt_f32_e32 vcc, s90, v98
	v_mul_f32_e32 v99, 0x4b800000, v98
	s_nop 0
	v_cndmask_b32_e32 v98, v98, v99, vcc
	v_rsq_f32_e32 v98, v98
	s_nop 0
	v_mul_f32_e32 v99, 0x45800000, v98
	v_cndmask_b32_e32 v98, v98, v99, vcc
	v_mul_f32_e32 v94, v94, v98
	v_mul_f32_e32 v94, v2, v94
	v_mul_f32_e32 v95, v95, v98
	v_fma_f32 v99, v166, v94, 0
	v_fma_f32 v94, v158, v94, 0
	v_mul_f32_e32 v95, v3, v95
	v_fmac_f32_e32 v99, v167, v95
	v_fmac_f32_e32 v94, v159, v95
	v_mul_f32_e32 v95, v96, v98
	v_mul_f32_e32 v95, v4, v95
	v_fmac_f32_e32 v99, v168, v95
	v_fmac_f32_e32 v94, v160, v95
	v_mul_f32_e32 v95, v97, v98
	v_mul_f32_e32 v95, v5, v95
	v_mul_f32_e32 v90, v90, v98
	v_fmac_f32_e32 v99, v169, v95
	v_fmac_f32_e32 v94, v161, v95
	v_mul_f32_e32 v90, v6, v90
	v_fmac_f32_e32 v99, v170, v90
	v_fmac_f32_e32 v94, v162, v90
	v_mul_f32_e32 v90, v91, v98
	v_mul_f32_e32 v90, v7, v90
	v_fmac_f32_e32 v99, v171, v90
	v_fmac_f32_e32 v94, v163, v90
	v_mul_f32_e32 v90, v92, v98
	v_mul_f32_e32 v90, v8, v90
	v_fmac_f32_e32 v99, v172, v90
	v_fmac_f32_e32 v94, v164, v90
	v_mul_f32_e32 v90, v93, v98
	v_mul_f32_e32 v90, v9, v90
	v_mul_f32_e32 v86, v86, v98
	v_fmac_f32_e32 v99, v173, v90
	v_fmac_f32_e32 v94, v165, v90
	v_mul_f32_e32 v86, v10, v86
	v_fmac_f32_e32 v99, v174, v86
	v_fmac_f32_e32 v94, v175, v86
	v_mul_f32_e32 v86, v87, v98
	v_mul_f32_e32 v86, v11, v86
	v_fmac_f32_e32 v99, v176, v86
	v_fmac_f32_e32 v94, v177, v86
	v_mul_f32_e32 v86, v88, v98
	v_mul_f32_e32 v86, v12, v86
	v_fmac_f32_e32 v99, v178, v86
	v_fmac_f32_e32 v94, v179, v86
	v_mul_f32_e32 v86, v89, v98
	v_mul_f32_e32 v86, v13, v86
	v_mul_f32_e32 v82, v82, v98
	v_fmac_f32_e32 v99, v180, v86
	v_fmac_f32_e32 v94, v181, v86
	v_mul_f32_e32 v82, v14, v82
	v_fmac_f32_e32 v99, v216, v82
	v_fmac_f32_e32 v94, v217, v82
	v_mul_f32_e32 v82, v83, v98
	v_mul_f32_e32 v82, v15, v82
	v_fmac_f32_e32 v99, v218, v82
	v_fmac_f32_e32 v94, v219, v82
	v_mul_f32_e32 v82, v84, v98
	v_mul_f32_e32 v82, v16, v82
	v_fmac_f32_e32 v99, v220, v82
	v_fmac_f32_e32 v94, v221, v82
	v_mul_f32_e32 v82, v85, v98
	v_mul_f32_e32 v82, v17, v82
	v_fmac_f32_e32 v99, v234, v82
	v_fmac_f32_e32 v94, v235, v82
	v_mul_f32_e32 v82, v157, v249
	v_fma_f32 v82, v156, v248, -v82
	v_add_f32_e32 v86, v82, v99
	v_mul_f32_e32 v82, v156, v249
	v_fmac_f32_e32 v82, v157, v248
	v_add_f32_e32 v87, v82, v94
	v_lshl_add_u64 v[82:83], v[150:151], 0, s[56:57]
	v_add_co_u32_e32 v84, vcc, s97, v82
	v_mul_f32_e32 v88, v192, v87
	s_nop 0
	v_addc_co_u32_e32 v85, vcc, 0, v83, vcc
	v_add_co_u32_e32 v82, vcc, s88, v82
	global_store_dword v[84:85], v86, off
	s_nop 0
	v_addc_co_u32_e32 v83, vcc, 0, v83, vcc
	global_store_dword v[82:83], v87, off
	v_mul_f32_e32 v82, v190, v87
	v_mul_f32_e32 v84, v191, v87
	v_mul_f32_e32 v90, v193, v87
	v_mul_f32_e32 v92, v194, v87
	v_mul_f32_e32 v94, v195, v87
	v_mul_f32_e32 v96, v196, v87
	v_mul_f32_e32 v99, v197, v87
	v_mul_f32_e32 v101, v206, v87
	v_mul_f32_e32 v103, v207, v87
	v_mul_f32_e32 v105, v208, v87
	v_mul_f32_e32 v107, v209, v87
	v_mul_f32_e32 v109, v210, v87
	v_mul_f32_e32 v111, v211, v87
	v_mul_f32_e32 v113, v212, v87
	v_mul_f32_e32 v87, v213, v87
	v_fma_f32 v82, v182, v86, -v82
	v_fma_f32 v84, v183, v86, -v84
	v_fma_f32 v88, v184, v86, -v88
	v_fma_f32 v90, v185, v86, -v90
	v_fma_f32 v92, v186, v86, -v92
	v_fma_f32 v94, v187, v86, -v94
	v_fma_f32 v96, v188, v86, -v96
	v_fma_f32 v99, v189, v86, -v99
	v_fma_f32 v101, v198, v86, -v101
	v_fma_f32 v103, v199, v86, -v103
	v_fma_f32 v105, v200, v86, -v105
	v_fma_f32 v107, v201, v86, -v107
	v_fma_f32 v109, v202, v86, -v109
	v_fma_f32 v111, v203, v86, -v111
	v_fma_f32 v113, v204, v86, -v113
	v_fma_f32 v86, v205, v86, -v87
	v_add_f32_dpp v82, v82, v82 quad_perm:[1,0,3,2] row_mask:0xf bank_mask:0xf
	v_add_f32_dpp v84, v84, v84 quad_perm:[1,0,3,2] row_mask:0xf bank_mask:0xf
	v_add_f32_dpp v88, v88, v88 quad_perm:[1,0,3,2] row_mask:0xf bank_mask:0xf
	v_add_f32_dpp v90, v90, v90 quad_perm:[1,0,3,2] row_mask:0xf bank_mask:0xf
	v_add_f32_dpp v92, v92, v92 quad_perm:[1,0,3,2] row_mask:0xf bank_mask:0xf
	v_add_f32_dpp v94, v94, v94 quad_perm:[1,0,3,2] row_mask:0xf bank_mask:0xf
	v_add_f32_dpp v96, v96, v96 quad_perm:[1,0,3,2] row_mask:0xf bank_mask:0xf
	v_add_f32_dpp v99, v99, v99 quad_perm:[1,0,3,2] row_mask:0xf bank_mask:0xf
	v_add_f32_dpp v101, v101, v101 quad_perm:[1,0,3,2] row_mask:0xf bank_mask:0xf
	v_add_f32_dpp v103, v103, v103 quad_perm:[1,0,3,2] row_mask:0xf bank_mask:0xf
	v_add_f32_dpp v105, v105, v105 quad_perm:[1,0,3,2] row_mask:0xf bank_mask:0xf
	v_add_f32_dpp v107, v107, v107 quad_perm:[1,0,3,2] row_mask:0xf bank_mask:0xf
	v_add_f32_dpp v109, v109, v109 quad_perm:[1,0,3,2] row_mask:0xf bank_mask:0xf
	v_add_f32_dpp v111, v111, v111 quad_perm:[1,0,3,2] row_mask:0xf bank_mask:0xf
	v_add_f32_dpp v113, v113, v113 quad_perm:[1,0,3,2] row_mask:0xf bank_mask:0xf
	s_nop 1
	v_add_f32_dpp v86, v86, v86 quad_perm:[1,0,3,2] row_mask:0xf bank_mask:0xf
	v_add_f32_dpp v82, v82, v82 quad_perm:[2,3,0,1] row_mask:0xf bank_mask:0xf
	v_add_f32_dpp v84, v84, v84 quad_perm:[2,3,0,1] row_mask:0xf bank_mask:0xf
	v_add_f32_dpp v88, v88, v88 quad_perm:[2,3,0,1] row_mask:0xf bank_mask:0xf
	v_add_f32_dpp v90, v90, v90 quad_perm:[2,3,0,1] row_mask:0xf bank_mask:0xf
	v_add_f32_dpp v92, v92, v92 quad_perm:[2,3,0,1] row_mask:0xf bank_mask:0xf
	v_add_f32_dpp v94, v94, v94 quad_perm:[2,3,0,1] row_mask:0xf bank_mask:0xf
	v_add_f32_dpp v96, v96, v96 quad_perm:[2,3,0,1] row_mask:0xf bank_mask:0xf
	v_add_f32_dpp v99, v99, v99 quad_perm:[2,3,0,1] row_mask:0xf bank_mask:0xf
	v_add_f32_dpp v101, v101, v101 quad_perm:[2,3,0,1] row_mask:0xf bank_mask:0xf
	v_add_f32_dpp v103, v103, v103 quad_perm:[2,3,0,1] row_mask:0xf bank_mask:0xf
	v_add_f32_dpp v105, v105, v105 quad_perm:[2,3,0,1] row_mask:0xf bank_mask:0xf
	v_add_f32_dpp v107, v107, v107 quad_perm:[2,3,0,1] row_mask:0xf bank_mask:0xf
	v_add_f32_dpp v109, v109, v109 quad_perm:[2,3,0,1] row_mask:0xf bank_mask:0xf
	v_add_f32_dpp v111, v111, v111 quad_perm:[2,3,0,1] row_mask:0xf bank_mask:0xf
	v_add_f32_dpp v113, v113, v113 quad_perm:[2,3,0,1] row_mask:0xf bank_mask:0xf
	s_nop 1
	v_add_f32_dpp v86, v86, v86 quad_perm:[2,3,0,1] row_mask:0xf bank_mask:0xf
	v_add_f32_dpp v82, v82, v82 row_half_mirror row_mask:0xf bank_mask:0xf
	v_add_f32_dpp v84, v84, v84 row_half_mirror row_mask:0xf bank_mask:0xf
	v_add_f32_dpp v88, v88, v88 row_half_mirror row_mask:0xf bank_mask:0xf
	v_add_f32_dpp v90, v90, v90 row_half_mirror row_mask:0xf bank_mask:0xf
	v_add_f32_dpp v92, v92, v92 row_half_mirror row_mask:0xf bank_mask:0xf
	v_add_f32_dpp v94, v94, v94 row_half_mirror row_mask:0xf bank_mask:0xf
	v_add_f32_dpp v96, v96, v96 row_half_mirror row_mask:0xf bank_mask:0xf
	v_add_f32_dpp v99, v99, v99 row_half_mirror row_mask:0xf bank_mask:0xf
	v_add_f32_dpp v101, v101, v101 row_half_mirror row_mask:0xf bank_mask:0xf
	v_add_f32_dpp v103, v103, v103 row_half_mirror row_mask:0xf bank_mask:0xf
	v_add_f32_dpp v105, v105, v105 row_half_mirror row_mask:0xf bank_mask:0xf
	v_add_f32_dpp v107, v107, v107 row_half_mirror row_mask:0xf bank_mask:0xf
	v_add_f32_dpp v109, v109, v109 row_half_mirror row_mask:0xf bank_mask:0xf
	v_add_f32_dpp v111, v111, v111 row_half_mirror row_mask:0xf bank_mask:0xf
	v_add_f32_dpp v113, v113, v113 row_half_mirror row_mask:0xf bank_mask:0xf
	s_nop 1
	v_add_f32_dpp v86, v86, v86 row_half_mirror row_mask:0xf bank_mask:0xf
	v_add_f32_dpp v82, v82, v82 row_mirror row_mask:0xf bank_mask:0xf
	v_add_f32_dpp v84, v84, v84 row_mirror row_mask:0xf bank_mask:0xf
	v_add_f32_dpp v88, v88, v88 row_mirror row_mask:0xf bank_mask:0xf
	v_add_f32_dpp v90, v90, v90 row_mirror row_mask:0xf bank_mask:0xf
	v_add_f32_dpp v92, v92, v92 row_mirror row_mask:0xf bank_mask:0xf
	v_add_f32_dpp v94, v94, v94 row_mirror row_mask:0xf bank_mask:0xf
	v_add_f32_dpp v96, v96, v96 row_mirror row_mask:0xf bank_mask:0xf
	v_add_f32_dpp v99, v99, v99 row_mirror row_mask:0xf bank_mask:0xf
	v_add_f32_dpp v101, v101, v101 row_mirror row_mask:0xf bank_mask:0xf
	v_add_f32_dpp v103, v103, v103 row_mirror row_mask:0xf bank_mask:0xf
	v_add_f32_dpp v105, v105, v105 row_mirror row_mask:0xf bank_mask:0xf
	v_add_f32_dpp v107, v107, v107 row_mirror row_mask:0xf bank_mask:0xf
	v_add_f32_dpp v109, v109, v109 row_mirror row_mask:0xf bank_mask:0xf
	v_add_f32_dpp v111, v111, v111 row_mirror row_mask:0xf bank_mask:0xf
	v_add_f32_dpp v113, v113, v113 row_mirror row_mask:0xf bank_mask:0xf
	s_nop 1
	v_add_f32_dpp v86, v86, v86 row_mirror row_mask:0xf bank_mask:0xf
	s_nop 1
	v_cndmask_b32_e64 v82, 0, v82, s[38:39]
	v_cndmask_b32_e64 v82, v82, v84, s[36:37]
	v_cndmask_b32_e64 v82, v82, v88, s[34:35]
	v_cndmask_b32_e64 v82, v82, v90, s[30:31]
	v_cndmask_b32_e64 v82, v82, v92, s[28:29]
	v_cndmask_b32_e64 v82, v82, v94, s[26:27]
	v_cndmask_b32_e64 v82, v82, v96, s[24:25]
	v_cndmask_b32_e64 v82, v82, v99, s[22:23]
	v_cndmask_b32_e64 v82, v82, v101, s[20:21]
	v_cndmask_b32_e64 v82, v82, v103, s[18:19]
	v_cndmask_b32_e64 v82, v82, v105, s[16:17]
	v_cndmask_b32_e64 v82, v82, v107, s[14:15]
	v_cndmask_b32_e64 v82, v82, v109, s[12:13]
	v_cndmask_b32_e64 v82, v82, v111, s[10:11]
	v_cndmask_b32_e64 v82, v82, v113, s[8:9]
	v_cndmask_b32_e64 v82, v82, v86, s[6:7]
	v_mov_b32_e32 v83, v82
	s_nop 1
	v_permlane16_swap_b32 v83, v82
	v_add_f32_e32 v82, v82, v83
	v_mov_b32_e32 v83, v82
	s_nop 1
	v_permlane32_swap_b32 v83, v82
	v_add_f32_e32 v82, v82, v83
	s_and_saveexec_b64 s[78:79], s[4:5]
	s_cbranch_execz .LBB0_258
	v_mul_f32_e32 v83, v247, v98
	v_mul_f32_e32 v83, v214, v83
	v_fmac_f32_e32 v82, v215, v83
	v_mul_f32_e32 v83, 0x3d372713, v82
	v_mul_f32_e32 v83, v82, v83
	v_fma_f32 v83, v82, v83, v82
	v_mul_f32_e32 v83, 0xbfcc422a, v83
	v_mul_f32_e32 v83, 0x3fb8aa3b, v83
	v_exp_f32_e32 v83, v83
	s_ashr_i32 s3, s2, 31
	s_lshl_b64 s[2:3], s[2:3], 12
	v_add_f32_e32 v83, 1.0, v83
	v_rcp_f32_e32 v83, v83
	s_nop 0
	v_mul_f32_e32 v84, v82, v83
	v_lshl_add_u64 v[82:83], v[152:153], 0, s[2:3]
	global_store_dword v[82:83], v84, off

.LBB0_259:
	v_pk_mul_f32 v[80:81], v[80:81], v[80:81]
	v_pk_mul_f32 v[78:79], v[78:79], v[78:79]
	v_pk_mul_f32 v[76:77], v[76:77], v[76:77]
	v_pk_mul_f32 v[74:75], v[74:75], v[74:75]
	s_waitcnt lgkmcnt(14)
	v_pk_mov_b32 v[82:83], v[78:79], v[80:81] op_sel:[1,0]
	v_mov_b32_e32 v79, v81
	v_pk_mov_b32 v[80:81], v[74:75], v[76:77] op_sel:[1,0]
	v_mov_b32_e32 v75, v77
	v_pk_add_f32 v[78:79], v[82:83], v[78:79]
	v_pk_add_f32 v[74:75], v[80:81], v[74:75]
	v_mul_f32_e32 v76, v70, v70
	v_mul_f32_e32 v77, v71, v71
	v_mul_f32_e32 v80, v72, v72
	v_mul_f32_e32 v81, v73, v73
	v_pk_add_f32 v[70:71], v[78:79], v[78:79] op_sel:[0,1] op_sel_hi:[1,0]
	v_pk_add_f32 v[72:73], v[74:75], v[74:75] op_sel:[0,1] op_sel_hi:[1,0]
	v_mov_b32_e32 v71, v76
	v_mov_b32_e32 v73, v77
	v_pk_add_f32 v[70:71], v[70:71], v[72:73]
	v_mul_f32_e32 v72, v67, v67
	v_pk_fma_f32 v[66:67], v[66:67], v[66:67], v[72:73] op_sel_hi:[1,1,0]
	v_mul_f32_e32 v72, v69, v69
	v_pk_fma_f32 v[68:69], v[68:69], v[68:69], v[72:73] op_sel_hi:[1,1,0]
	v_mov_b32_e32 v67, v80
	v_mov_b32_e32 v69, v81
	v_pk_add_f32 v[66:67], v[66:67], v[68:69]
	s_add_i32 s2, s72, s40
	v_pk_add_f32 v[66:67], v[70:71], v[66:67]
	s_ashr_i32 s3, s2, 31
	v_add_f32_e32 v66, v66, v67
	s_lshl_b64 s[2:3], s[2:3], 14
	s_nop 1
	v_add_f32_dpp v66, v66, v66 quad_perm:[1,0,3,2] row_mask:0xf bank_mask:0xf
	s_nop 1
	v_add_f32_dpp v66, v66, v66 quad_perm:[2,3,0,1] row_mask:0xf bank_mask:0xf
	s_nop 1
	v_add_f32_dpp v66, v66, v66 row_half_mirror row_mask:0xf bank_mask:0xf
	s_nop 1
	v_add_f32_dpp v66, v66, v66 row_mirror row_mask:0xf bank_mask:0xf
	v_mov_b32_e32 v67, v66
	s_nop 1
	v_permlane16_swap_b32 v67, v66
	v_add_f32_e32 v66, v66, v67
	v_mov_b32_e32 v67, v66
	s_nop 1
	v_permlane32_swap_b32 v67, v66
	v_add_f32_e32 v66, v66, v67
	v_fmamk_f32 v66, v66, 0x3a800000, v225
	v_cmp_gt_f32_e32 vcc, s90, v66
	v_mul_f32_e32 v67, 0x4b800000, v66
	s_nop 0
	v_cndmask_b32_e32 v66, v66, v67, vcc
	v_rsq_f32_e32 v66, v66
	s_nop 0
	v_mul_f32_e32 v67, 0x45800000, v66
	v_cndmask_b32_e32 v66, v66, v67, vcc
	v_mul_f32_e32 v62, v62, v66
	v_mul_f32_e32 v62, v2, v62
	v_mul_f32_e32 v63, v63, v66
	v_fma_f32 v67, v166, v62, 0
	v_fma_f32 v62, v158, v62, 0
	v_mul_f32_e32 v63, v3, v63
	v_fmac_f32_e32 v67, v167, v63
	v_fmac_f32_e32 v62, v159, v63
	v_mul_f32_e32 v63, v64, v66
	v_mul_f32_e32 v63, v4, v63
	v_fmac_f32_e32 v67, v168, v63
	v_fmac_f32_e32 v62, v160, v63
	v_mul_f32_e32 v63, v65, v66
	v_mul_f32_e32 v63, v5, v63
	v_mul_f32_e32 v58, v58, v66
	v_fmac_f32_e32 v67, v169, v63
	v_fmac_f32_e32 v62, v161, v63
	v_mul_f32_e32 v58, v6, v58
	v_fmac_f32_e32 v67, v170, v58
	v_fmac_f32_e32 v62, v162, v58
	v_mul_f32_e32 v58, v59, v66
	v_mul_f32_e32 v58, v7, v58
	v_fmac_f32_e32 v67, v171, v58
	v_fmac_f32_e32 v62, v163, v58
	v_mul_f32_e32 v58, v60, v66
	v_mul_f32_e32 v58, v8, v58
	v_fmac_f32_e32 v67, v172, v58
	v_fmac_f32_e32 v62, v164, v58
	v_mul_f32_e32 v58, v61, v66
	v_mul_f32_e32 v58, v9, v58
	v_mul_f32_e32 v54, v54, v66
	v_fmac_f32_e32 v67, v173, v58
	v_fmac_f32_e32 v62, v165, v58
	v_mul_f32_e32 v54, v10, v54
	v_fmac_f32_e32 v67, v174, v54
	v_fmac_f32_e32 v62, v175, v54
	v_mul_f32_e32 v54, v55, v66
	v_mul_f32_e32 v54, v11, v54
	v_fmac_f32_e32 v67, v176, v54
	v_fmac_f32_e32 v62, v177, v54
	v_mul_f32_e32 v54, v56, v66
	v_mul_f32_e32 v54, v12, v54
	v_fmac_f32_e32 v67, v178, v54
	v_fmac_f32_e32 v62, v179, v54
	v_mul_f32_e32 v54, v57, v66
	v_mul_f32_e32 v54, v13, v54
	v_mul_f32_e32 v50, v50, v66
	v_fmac_f32_e32 v67, v180, v54
	v_fmac_f32_e32 v62, v181, v54
	v_mul_f32_e32 v50, v14, v50
	v_fmac_f32_e32 v67, v216, v50
	v_fmac_f32_e32 v62, v217, v50
	v_mul_f32_e32 v50, v51, v66
	v_mul_f32_e32 v50, v15, v50
	v_fmac_f32_e32 v67, v218, v50
	v_fmac_f32_e32 v62, v219, v50
	v_mul_f32_e32 v50, v52, v66
	v_mul_f32_e32 v50, v16, v50
	v_fmac_f32_e32 v67, v220, v50
	v_fmac_f32_e32 v62, v221, v50
	v_mul_f32_e32 v50, v53, v66
	v_mul_f32_e32 v50, v17, v50
	v_fmac_f32_e32 v67, v234, v50
	v_fmac_f32_e32 v62, v235, v50
	v_mul_f32_e32 v50, v157, v246
	v_fma_f32 v50, v156, v245, -v50
	v_add_f32_e32 v54, v50, v67
	v_mul_f32_e32 v50, v156, v246
	v_fmac_f32_e32 v50, v157, v245
	v_add_f32_e32 v55, v50, v62
	v_lshl_add_u64 v[50:51], v[150:151], 0, s[2:3]
	v_add_co_u32_e32 v52, vcc, s97, v50
	v_mul_f32_e32 v56, v192, v55
	s_nop 0
	v_addc_co_u32_e32 v53, vcc, 0, v51, vcc
	v_add_co_u32_e32 v50, vcc, s88, v50
	global_store_dword v[52:53], v54, off
	s_nop 0
	v_addc_co_u32_e32 v51, vcc, 0, v51, vcc
	global_store_dword v[50:51], v55, off
	v_mul_f32_e32 v50, v190, v55
	v_mul_f32_e32 v52, v191, v55
	v_mul_f32_e32 v58, v193, v55
	v_mul_f32_e32 v60, v194, v55
	v_mul_f32_e32 v62, v195, v55
	v_mul_f32_e32 v64, v196, v55
	v_mul_f32_e32 v67, v197, v55
	v_mul_f32_e32 v69, v206, v55
	v_mul_f32_e32 v71, v207, v55
	v_mul_f32_e32 v73, v208, v55
	v_mul_f32_e32 v75, v209, v55
	v_mul_f32_e32 v77, v210, v55
	v_mul_f32_e32 v79, v211, v55
	v_mul_f32_e32 v81, v212, v55
	v_mul_f32_e32 v55, v213, v55
	v_fma_f32 v50, v182, v54, -v50
	v_fma_f32 v52, v183, v54, -v52
	v_fma_f32 v56, v184, v54, -v56
	v_fma_f32 v58, v185, v54, -v58
	v_fma_f32 v60, v186, v54, -v60
	v_fma_f32 v62, v187, v54, -v62
	v_fma_f32 v64, v188, v54, -v64
	v_fma_f32 v67, v189, v54, -v67
	v_fma_f32 v69, v198, v54, -v69
	v_fma_f32 v71, v199, v54, -v71
	v_fma_f32 v73, v200, v54, -v73
	v_fma_f32 v75, v201, v54, -v75
	v_fma_f32 v77, v202, v54, -v77
	v_fma_f32 v79, v203, v54, -v79
	v_fma_f32 v81, v204, v54, -v81
	v_fma_f32 v54, v205, v54, -v55
	v_add_f32_dpp v50, v50, v50 quad_perm:[1,0,3,2] row_mask:0xf bank_mask:0xf
	v_add_f32_dpp v52, v52, v52 quad_perm:[1,0,3,2] row_mask:0xf bank_mask:0xf
	v_add_f32_dpp v56, v56, v56 quad_perm:[1,0,3,2] row_mask:0xf bank_mask:0xf
	v_add_f32_dpp v58, v58, v58 quad_perm:[1,0,3,2] row_mask:0xf bank_mask:0xf
	v_add_f32_dpp v60, v60, v60 quad_perm:[1,0,3,2] row_mask:0xf bank_mask:0xf
	v_add_f32_dpp v62, v62, v62 quad_perm:[1,0,3,2] row_mask:0xf bank_mask:0xf
	v_add_f32_dpp v64, v64, v64 quad_perm:[1,0,3,2] row_mask:0xf bank_mask:0xf
	v_add_f32_dpp v67, v67, v67 quad_perm:[1,0,3,2] row_mask:0xf bank_mask:0xf
	v_add_f32_dpp v69, v69, v69 quad_perm:[1,0,3,2] row_mask:0xf bank_mask:0xf
	v_add_f32_dpp v71, v71, v71 quad_perm:[1,0,3,2] row_mask:0xf bank_mask:0xf
	v_add_f32_dpp v73, v73, v73 quad_perm:[1,0,3,2] row_mask:0xf bank_mask:0xf
	v_add_f32_dpp v75, v75, v75 quad_perm:[1,0,3,2] row_mask:0xf bank_mask:0xf
	v_add_f32_dpp v77, v77, v77 quad_perm:[1,0,3,2] row_mask:0xf bank_mask:0xf
	v_add_f32_dpp v79, v79, v79 quad_perm:[1,0,3,2] row_mask:0xf bank_mask:0xf
	v_add_f32_dpp v81, v81, v81 quad_perm:[1,0,3,2] row_mask:0xf bank_mask:0xf
	s_nop 1
	v_add_f32_dpp v54, v54, v54 quad_perm:[1,0,3,2] row_mask:0xf bank_mask:0xf
	v_add_f32_dpp v50, v50, v50 quad_perm:[2,3,0,1] row_mask:0xf bank_mask:0xf
	v_add_f32_dpp v52, v52, v52 quad_perm:[2,3,0,1] row_mask:0xf bank_mask:0xf
	v_add_f32_dpp v56, v56, v56 quad_perm:[2,3,0,1] row_mask:0xf bank_mask:0xf
	v_add_f32_dpp v58, v58, v58 quad_perm:[2,3,0,1] row_mask:0xf bank_mask:0xf
	v_add_f32_dpp v60, v60, v60 quad_perm:[2,3,0,1] row_mask:0xf bank_mask:0xf
	v_add_f32_dpp v62, v62, v62 quad_perm:[2,3,0,1] row_mask:0xf bank_mask:0xf
	v_add_f32_dpp v64, v64, v64 quad_perm:[2,3,0,1] row_mask:0xf bank_mask:0xf
	v_add_f32_dpp v67, v67, v67 quad_perm:[2,3,0,1] row_mask:0xf bank_mask:0xf
	v_add_f32_dpp v69, v69, v69 quad_perm:[2,3,0,1] row_mask:0xf bank_mask:0xf
	v_add_f32_dpp v71, v71, v71 quad_perm:[2,3,0,1] row_mask:0xf bank_mask:0xf
	v_add_f32_dpp v73, v73, v73 quad_perm:[2,3,0,1] row_mask:0xf bank_mask:0xf
	v_add_f32_dpp v75, v75, v75 quad_perm:[2,3,0,1] row_mask:0xf bank_mask:0xf
	v_add_f32_dpp v77, v77, v77 quad_perm:[2,3,0,1] row_mask:0xf bank_mask:0xf
	v_add_f32_dpp v79, v79, v79 quad_perm:[2,3,0,1] row_mask:0xf bank_mask:0xf
	v_add_f32_dpp v81, v81, v81 quad_perm:[2,3,0,1] row_mask:0xf bank_mask:0xf
	s_nop 1
	v_add_f32_dpp v54, v54, v54 quad_perm:[2,3,0,1] row_mask:0xf bank_mask:0xf
	v_add_f32_dpp v50, v50, v50 row_half_mirror row_mask:0xf bank_mask:0xf
	v_add_f32_dpp v52, v52, v52 row_half_mirror row_mask:0xf bank_mask:0xf
	v_add_f32_dpp v56, v56, v56 row_half_mirror row_mask:0xf bank_mask:0xf
	v_add_f32_dpp v58, v58, v58 row_half_mirror row_mask:0xf bank_mask:0xf
	v_add_f32_dpp v60, v60, v60 row_half_mirror row_mask:0xf bank_mask:0xf
	v_add_f32_dpp v62, v62, v62 row_half_mirror row_mask:0xf bank_mask:0xf
	v_add_f32_dpp v64, v64, v64 row_half_mirror row_mask:0xf bank_mask:0xf
	v_add_f32_dpp v67, v67, v67 row_half_mirror row_mask:0xf bank_mask:0xf
	v_add_f32_dpp v69, v69, v69 row_half_mirror row_mask:0xf bank_mask:0xf
	v_add_f32_dpp v71, v71, v71 row_half_mirror row_mask:0xf bank_mask:0xf
	v_add_f32_dpp v73, v73, v73 row_half_mirror row_mask:0xf bank_mask:0xf
	v_add_f32_dpp v75, v75, v75 row_half_mirror row_mask:0xf bank_mask:0xf
	v_add_f32_dpp v77, v77, v77 row_half_mirror row_mask:0xf bank_mask:0xf
	v_add_f32_dpp v79, v79, v79 row_half_mirror row_mask:0xf bank_mask:0xf
	v_add_f32_dpp v81, v81, v81 row_half_mirror row_mask:0xf bank_mask:0xf
	s_nop 1
	v_add_f32_dpp v54, v54, v54 row_half_mirror row_mask:0xf bank_mask:0xf
	v_add_f32_dpp v50, v50, v50 row_mirror row_mask:0xf bank_mask:0xf
	v_add_f32_dpp v52, v52, v52 row_mirror row_mask:0xf bank_mask:0xf
	v_add_f32_dpp v56, v56, v56 row_mirror row_mask:0xf bank_mask:0xf
	v_add_f32_dpp v58, v58, v58 row_mirror row_mask:0xf bank_mask:0xf
	v_add_f32_dpp v60, v60, v60 row_mirror row_mask:0xf bank_mask:0xf
	v_add_f32_dpp v62, v62, v62 row_mirror row_mask:0xf bank_mask:0xf
	v_add_f32_dpp v64, v64, v64 row_mirror row_mask:0xf bank_mask:0xf
	v_add_f32_dpp v67, v67, v67 row_mirror row_mask:0xf bank_mask:0xf
	v_add_f32_dpp v69, v69, v69 row_mirror row_mask:0xf bank_mask:0xf
	v_add_f32_dpp v71, v71, v71 row_mirror row_mask:0xf bank_mask:0xf
	v_add_f32_dpp v73, v73, v73 row_mirror row_mask:0xf bank_mask:0xf
	v_add_f32_dpp v75, v75, v75 row_mirror row_mask:0xf bank_mask:0xf
	v_add_f32_dpp v77, v77, v77 row_mirror row_mask:0xf bank_mask:0xf
	v_add_f32_dpp v79, v79, v79 row_mirror row_mask:0xf bank_mask:0xf
	v_add_f32_dpp v81, v81, v81 row_mirror row_mask:0xf bank_mask:0xf
	s_nop 1
	v_add_f32_dpp v54, v54, v54 row_mirror row_mask:0xf bank_mask:0xf
	s_nop 1
	v_cndmask_b32_e64 v50, 0, v50, s[38:39]
	v_cndmask_b32_e64 v50, v50, v52, s[36:37]
	v_cndmask_b32_e64 v50, v50, v56, s[34:35]
	v_cndmask_b32_e64 v50, v50, v58, s[30:31]
	v_cndmask_b32_e64 v50, v50, v60, s[28:29]
	v_cndmask_b32_e64 v50, v50, v62, s[26:27]
	v_cndmask_b32_e64 v50, v50, v64, s[24:25]
	v_cndmask_b32_e64 v50, v50, v67, s[22:23]
	v_cndmask_b32_e64 v50, v50, v69, s[20:21]
	v_cndmask_b32_e64 v50, v50, v71, s[18:19]
	v_cndmask_b32_e64 v50, v50, v73, s[16:17]
	v_cndmask_b32_e64 v50, v50, v75, s[14:15]
	v_cndmask_b32_e64 v50, v50, v77, s[12:13]
	v_cndmask_b32_e64 v50, v50, v79, s[10:11]
	v_cndmask_b32_e64 v50, v50, v81, s[8:9]
	v_cndmask_b32_e64 v50, v50, v54, s[6:7]
	v_mov_b32_e32 v51, v50
	s_nop 1
	v_permlane16_swap_b32 v51, v50
	v_add_f32_e32 v50, v50, v51
	v_mov_b32_e32 v51, v50
	s_nop 1
	v_permlane32_swap_b32 v51, v50
	v_add_f32_e32 v50, v50, v51
	s_and_saveexec_b64 s[2:3], s[4:5]
	s_cbranch_execz .LBB0_261
	v_mul_f32_e32 v51, v244, v66
	v_mul_f32_e32 v51, v214, v51
	v_fmac_f32_e32 v50, v215, v51
	v_mul_f32_e32 v51, 0x3d372713, v50
	v_mul_f32_e32 v51, v50, v51
	v_fma_f32 v51, v50, v51, v50
	v_mul_f32_e32 v51, 0xbfcc422a, v51
	v_mul_f32_e32 v51, 0x3fb8aa3b, v51
	v_exp_f32_e32 v51, v51
	s_ashr_i32 s73, s72, 31
	s_lshl_b64 s[56:57], s[72:73], 12
	v_add_f32_e32 v51, 1.0, v51
	v_rcp_f32_e32 v51, v51
	s_nop 0
	v_mul_f32_e32 v52, v50, v51
	v_lshl_add_u64 v[50:51], v[152:153], 0, s[56:57]
	global_store_dword v[50:51], v52, off

.LBB0_262:
	v_pk_mul_f32 v[48:49], v[48:49], v[48:49]
	v_pk_mul_f32 v[46:47], v[46:47], v[46:47]
	v_pk_mul_f32 v[44:45], v[44:45], v[44:45]
	v_pk_mul_f32 v[42:43], v[42:43], v[42:43]
	s_waitcnt lgkmcnt(14)
	v_pk_mov_b32 v[50:51], v[46:47], v[48:49] op_sel:[1,0]
	v_mov_b32_e32 v47, v49
	v_pk_mov_b32 v[48:49], v[42:43], v[44:45] op_sel:[1,0]
	v_mov_b32_e32 v43, v45
	v_pk_add_f32 v[46:47], v[50:51], v[46:47]
	v_pk_add_f32 v[42:43], v[48:49], v[42:43]
	v_mul_f32_e32 v44, v38, v38
	v_mul_f32_e32 v45, v39, v39
	v_mul_f32_e32 v48, v40, v40
	v_mul_f32_e32 v49, v41, v41
	v_pk_add_f32 v[38:39], v[46:47], v[46:47] op_sel:[0,1] op_sel_hi:[1,0]
	v_pk_add_f32 v[40:41], v[42:43], v[42:43] op_sel:[0,1] op_sel_hi:[1,0]
	v_mov_b32_e32 v39, v44
	v_mov_b32_e32 v41, v45
	v_pk_add_f32 v[38:39], v[38:39], v[40:41]
	v_mul_f32_e32 v40, v35, v35
	v_pk_fma_f32 v[34:35], v[34:35], v[34:35], v[40:41] op_sel_hi:[1,1,0]
	v_mul_f32_e32 v40, v37, v37
	v_pk_fma_f32 v[36:37], v[36:37], v[36:37], v[40:41] op_sel_hi:[1,1,0]
	v_mov_b32_e32 v35, v48
	v_mov_b32_e32 v37, v49
	v_pk_add_f32 v[34:35], v[34:35], v[36:37]
	s_add_i32 s2, s70, s40
	v_pk_add_f32 v[34:35], v[38:39], v[34:35]
	s_ashr_i32 s3, s2, 31
	v_add_f32_e32 v34, v34, v35
	s_lshl_b64 s[2:3], s[2:3], 14
	s_nop 1
	v_add_f32_dpp v34, v34, v34 quad_perm:[1,0,3,2] row_mask:0xf bank_mask:0xf
	s_nop 1
	v_add_f32_dpp v34, v34, v34 quad_perm:[2,3,0,1] row_mask:0xf bank_mask:0xf
	s_nop 1
	v_add_f32_dpp v34, v34, v34 row_half_mirror row_mask:0xf bank_mask:0xf
	s_nop 1
	v_add_f32_dpp v34, v34, v34 row_mirror row_mask:0xf bank_mask:0xf
	v_mov_b32_e32 v35, v34
	s_nop 1
	v_permlane16_swap_b32 v35, v34
	v_add_f32_e32 v34, v34, v35
	v_mov_b32_e32 v35, v34
	s_nop 1
	v_permlane32_swap_b32 v35, v34
	v_add_f32_e32 v34, v34, v35
	v_fmamk_f32 v34, v34, 0x3a800000, v225
	v_cmp_gt_f32_e32 vcc, s90, v34
	v_mul_f32_e32 v35, 0x4b800000, v34
	s_nop 0
	v_cndmask_b32_e32 v34, v34, v35, vcc
	v_rsq_f32_e32 v34, v34
	s_nop 0
	v_mul_f32_e32 v35, 0x45800000, v34
	v_cndmask_b32_e32 v34, v34, v35, vcc
	v_mul_f32_e32 v30, v30, v34
	v_mul_f32_e32 v30, v2, v30
	v_mul_f32_e32 v31, v31, v34
	v_fma_f32 v35, v166, v30, 0
	v_fma_f32 v30, v158, v30, 0
	v_mul_f32_e32 v31, v3, v31
	v_fmac_f32_e32 v35, v167, v31
	v_fmac_f32_e32 v30, v159, v31
	v_mul_f32_e32 v31, v32, v34
	v_mul_f32_e32 v31, v4, v31
	v_fmac_f32_e32 v35, v168, v31
	v_fmac_f32_e32 v30, v160, v31
	v_mul_f32_e32 v31, v33, v34
	v_mul_f32_e32 v31, v5, v31
	v_mul_f32_e32 v26, v26, v34
	v_fmac_f32_e32 v35, v169, v31
	v_fmac_f32_e32 v30, v161, v31
	v_mul_f32_e32 v26, v6, v26
	v_fmac_f32_e32 v35, v170, v26
	v_fmac_f32_e32 v30, v162, v26
	v_mul_f32_e32 v26, v27, v34
	v_mul_f32_e32 v26, v7, v26
	v_fmac_f32_e32 v35, v171, v26
	v_fmac_f32_e32 v30, v163, v26
	v_mul_f32_e32 v26, v28, v34
	v_mul_f32_e32 v26, v8, v26
	v_fmac_f32_e32 v35, v172, v26
	v_fmac_f32_e32 v30, v164, v26
	v_mul_f32_e32 v26, v29, v34
	v_mul_f32_e32 v26, v9, v26
	v_mul_f32_e32 v22, v22, v34
	v_fmac_f32_e32 v35, v173, v26
	v_fmac_f32_e32 v30, v165, v26
	v_mul_f32_e32 v22, v10, v22
	v_fmac_f32_e32 v35, v174, v22
	v_fmac_f32_e32 v30, v175, v22
	v_mul_f32_e32 v22, v23, v34
	v_mul_f32_e32 v22, v11, v22
	v_fmac_f32_e32 v35, v176, v22
	v_fmac_f32_e32 v30, v177, v22
	v_mul_f32_e32 v22, v24, v34
	v_mul_f32_e32 v22, v12, v22
	v_fmac_f32_e32 v35, v178, v22
	v_fmac_f32_e32 v30, v179, v22
	v_mul_f32_e32 v22, v25, v34
	v_mul_f32_e32 v22, v13, v22
	v_mul_f32_e32 v18, v18, v34
	v_fmac_f32_e32 v35, v180, v22
	v_fmac_f32_e32 v30, v181, v22
	v_mul_f32_e32 v18, v14, v18
	v_fmac_f32_e32 v35, v216, v18
	v_fmac_f32_e32 v30, v217, v18
	v_mul_f32_e32 v18, v19, v34
	v_mul_f32_e32 v18, v15, v18
	v_fmac_f32_e32 v35, v218, v18
	v_fmac_f32_e32 v30, v219, v18
	v_mul_f32_e32 v18, v20, v34
	v_mul_f32_e32 v18, v16, v18
	v_fmac_f32_e32 v35, v220, v18
	v_fmac_f32_e32 v30, v221, v18
	v_mul_f32_e32 v18, v21, v34
	v_mul_f32_e32 v18, v17, v18
	v_fmac_f32_e32 v35, v234, v18
	v_fmac_f32_e32 v30, v235, v18
	v_mul_f32_e32 v18, v157, v243
	v_fma_f32 v18, v156, v228, -v18
	v_add_f32_e32 v22, v18, v35
	v_mul_f32_e32 v18, v156, v243
	v_fmac_f32_e32 v18, v157, v228
	v_add_f32_e32 v23, v18, v30
	v_lshl_add_u64 v[18:19], v[150:151], 0, s[2:3]
	v_add_co_u32_e32 v20, vcc, s97, v18
	v_mul_f32_e32 v24, v192, v23
	s_nop 0
	v_addc_co_u32_e32 v21, vcc, 0, v19, vcc
	v_add_co_u32_e32 v18, vcc, s88, v18
	global_store_dword v[20:21], v22, off
	s_nop 0
	v_addc_co_u32_e32 v19, vcc, 0, v19, vcc
	global_store_dword v[18:19], v23, off
	v_mul_f32_e32 v18, v190, v23
	v_mul_f32_e32 v20, v191, v23
	v_mul_f32_e32 v26, v193, v23
	v_mul_f32_e32 v28, v194, v23
	v_mul_f32_e32 v30, v195, v23
	v_mul_f32_e32 v32, v196, v23
	v_mul_f32_e32 v35, v197, v23
	v_mul_f32_e32 v37, v206, v23
	v_mul_f32_e32 v39, v207, v23
	v_mul_f32_e32 v41, v208, v23
	v_mul_f32_e32 v43, v209, v23
	v_mul_f32_e32 v45, v210, v23
	v_mul_f32_e32 v47, v211, v23
	v_mul_f32_e32 v49, v212, v23
	v_mul_f32_e32 v23, v213, v23
	v_fma_f32 v18, v182, v22, -v18
	v_fma_f32 v20, v183, v22, -v20
	v_fma_f32 v24, v184, v22, -v24
	v_fma_f32 v26, v185, v22, -v26
	v_fma_f32 v28, v186, v22, -v28
	v_fma_f32 v30, v187, v22, -v30
	v_fma_f32 v32, v188, v22, -v32
	v_fma_f32 v35, v189, v22, -v35
	v_fma_f32 v37, v198, v22, -v37
	v_fma_f32 v39, v199, v22, -v39
	v_fma_f32 v41, v200, v22, -v41
	v_fma_f32 v43, v201, v22, -v43
	v_fma_f32 v45, v202, v22, -v45
	v_fma_f32 v47, v203, v22, -v47
	v_fma_f32 v49, v204, v22, -v49
	v_fma_f32 v22, v205, v22, -v23
	v_add_f32_dpp v18, v18, v18 quad_perm:[1,0,3,2] row_mask:0xf bank_mask:0xf
	v_add_f32_dpp v20, v20, v20 quad_perm:[1,0,3,2] row_mask:0xf bank_mask:0xf
	v_add_f32_dpp v24, v24, v24 quad_perm:[1,0,3,2] row_mask:0xf bank_mask:0xf
	v_add_f32_dpp v26, v26, v26 quad_perm:[1,0,3,2] row_mask:0xf bank_mask:0xf
	v_add_f32_dpp v28, v28, v28 quad_perm:[1,0,3,2] row_mask:0xf bank_mask:0xf
	v_add_f32_dpp v30, v30, v30 quad_perm:[1,0,3,2] row_mask:0xf bank_mask:0xf
	v_add_f32_dpp v32, v32, v32 quad_perm:[1,0,3,2] row_mask:0xf bank_mask:0xf
	v_add_f32_dpp v35, v35, v35 quad_perm:[1,0,3,2] row_mask:0xf bank_mask:0xf
	v_add_f32_dpp v37, v37, v37 quad_perm:[1,0,3,2] row_mask:0xf bank_mask:0xf
	v_add_f32_dpp v39, v39, v39 quad_perm:[1,0,3,2] row_mask:0xf bank_mask:0xf
	v_add_f32_dpp v41, v41, v41 quad_perm:[1,0,3,2] row_mask:0xf bank_mask:0xf
	v_add_f32_dpp v43, v43, v43 quad_perm:[1,0,3,2] row_mask:0xf bank_mask:0xf
	v_add_f32_dpp v45, v45, v45 quad_perm:[1,0,3,2] row_mask:0xf bank_mask:0xf
	v_add_f32_dpp v47, v47, v47 quad_perm:[1,0,3,2] row_mask:0xf bank_mask:0xf
	v_add_f32_dpp v49, v49, v49 quad_perm:[1,0,3,2] row_mask:0xf bank_mask:0xf
	s_nop 1
	v_add_f32_dpp v22, v22, v22 quad_perm:[1,0,3,2] row_mask:0xf bank_mask:0xf
	v_add_f32_dpp v18, v18, v18 quad_perm:[2,3,0,1] row_mask:0xf bank_mask:0xf
	v_add_f32_dpp v20, v20, v20 quad_perm:[2,3,0,1] row_mask:0xf bank_mask:0xf
	v_add_f32_dpp v24, v24, v24 quad_perm:[2,3,0,1] row_mask:0xf bank_mask:0xf
	v_add_f32_dpp v26, v26, v26 quad_perm:[2,3,0,1] row_mask:0xf bank_mask:0xf
	v_add_f32_dpp v28, v28, v28 quad_perm:[2,3,0,1] row_mask:0xf bank_mask:0xf
	v_add_f32_dpp v30, v30, v30 quad_perm:[2,3,0,1] row_mask:0xf bank_mask:0xf
	v_add_f32_dpp v32, v32, v32 quad_perm:[2,3,0,1] row_mask:0xf bank_mask:0xf
	v_add_f32_dpp v35, v35, v35 quad_perm:[2,3,0,1] row_mask:0xf bank_mask:0xf
	v_add_f32_dpp v37, v37, v37 quad_perm:[2,3,0,1] row_mask:0xf bank_mask:0xf
	v_add_f32_dpp v39, v39, v39 quad_perm:[2,3,0,1] row_mask:0xf bank_mask:0xf
	v_add_f32_dpp v41, v41, v41 quad_perm:[2,3,0,1] row_mask:0xf bank_mask:0xf
	v_add_f32_dpp v43, v43, v43 quad_perm:[2,3,0,1] row_mask:0xf bank_mask:0xf
	v_add_f32_dpp v45, v45, v45 quad_perm:[2,3,0,1] row_mask:0xf bank_mask:0xf
	v_add_f32_dpp v47, v47, v47 quad_perm:[2,3,0,1] row_mask:0xf bank_mask:0xf
	v_add_f32_dpp v49, v49, v49 quad_perm:[2,3,0,1] row_mask:0xf bank_mask:0xf
	s_nop 1
	v_add_f32_dpp v22, v22, v22 quad_perm:[2,3,0,1] row_mask:0xf bank_mask:0xf
	v_add_f32_dpp v18, v18, v18 row_half_mirror row_mask:0xf bank_mask:0xf
	v_add_f32_dpp v20, v20, v20 row_half_mirror row_mask:0xf bank_mask:0xf
	v_add_f32_dpp v24, v24, v24 row_half_mirror row_mask:0xf bank_mask:0xf
	v_add_f32_dpp v26, v26, v26 row_half_mirror row_mask:0xf bank_mask:0xf
	v_add_f32_dpp v28, v28, v28 row_half_mirror row_mask:0xf bank_mask:0xf
	v_add_f32_dpp v30, v30, v30 row_half_mirror row_mask:0xf bank_mask:0xf
	v_add_f32_dpp v32, v32, v32 row_half_mirror row_mask:0xf bank_mask:0xf
	v_add_f32_dpp v35, v35, v35 row_half_mirror row_mask:0xf bank_mask:0xf
	v_add_f32_dpp v37, v37, v37 row_half_mirror row_mask:0xf bank_mask:0xf
	v_add_f32_dpp v39, v39, v39 row_half_mirror row_mask:0xf bank_mask:0xf
	v_add_f32_dpp v41, v41, v41 row_half_mirror row_mask:0xf bank_mask:0xf
	v_add_f32_dpp v43, v43, v43 row_half_mirror row_mask:0xf bank_mask:0xf
	v_add_f32_dpp v45, v45, v45 row_half_mirror row_mask:0xf bank_mask:0xf
	v_add_f32_dpp v47, v47, v47 row_half_mirror row_mask:0xf bank_mask:0xf
	v_add_f32_dpp v49, v49, v49 row_half_mirror row_mask:0xf bank_mask:0xf
	s_nop 1
	v_add_f32_dpp v22, v22, v22 row_half_mirror row_mask:0xf bank_mask:0xf
	v_add_f32_dpp v18, v18, v18 row_mirror row_mask:0xf bank_mask:0xf
	v_add_f32_dpp v20, v20, v20 row_mirror row_mask:0xf bank_mask:0xf
	v_add_f32_dpp v24, v24, v24 row_mirror row_mask:0xf bank_mask:0xf
	v_add_f32_dpp v26, v26, v26 row_mirror row_mask:0xf bank_mask:0xf
	v_add_f32_dpp v28, v28, v28 row_mirror row_mask:0xf bank_mask:0xf
	v_add_f32_dpp v30, v30, v30 row_mirror row_mask:0xf bank_mask:0xf
	v_add_f32_dpp v32, v32, v32 row_mirror row_mask:0xf bank_mask:0xf
	v_add_f32_dpp v35, v35, v35 row_mirror row_mask:0xf bank_mask:0xf
	v_add_f32_dpp v37, v37, v37 row_mirror row_mask:0xf bank_mask:0xf
	v_add_f32_dpp v39, v39, v39 row_mirror row_mask:0xf bank_mask:0xf
	v_add_f32_dpp v41, v41, v41 row_mirror row_mask:0xf bank_mask:0xf
	v_add_f32_dpp v43, v43, v43 row_mirror row_mask:0xf bank_mask:0xf
	v_add_f32_dpp v45, v45, v45 row_mirror row_mask:0xf bank_mask:0xf
	v_add_f32_dpp v47, v47, v47 row_mirror row_mask:0xf bank_mask:0xf
	v_add_f32_dpp v49, v49, v49 row_mirror row_mask:0xf bank_mask:0xf
	s_nop 1
	v_add_f32_dpp v22, v22, v22 row_mirror row_mask:0xf bank_mask:0xf
	s_nop 1
	v_cndmask_b32_e64 v18, 0, v18, s[38:39]
	v_cndmask_b32_e64 v18, v18, v20, s[36:37]
	v_cndmask_b32_e64 v18, v18, v24, s[34:35]
	v_cndmask_b32_e64 v18, v18, v26, s[30:31]
	v_cndmask_b32_e64 v18, v18, v28, s[28:29]
	v_cndmask_b32_e64 v18, v18, v30, s[26:27]
	v_cndmask_b32_e64 v18, v18, v32, s[24:25]
	v_cndmask_b32_e64 v18, v18, v35, s[22:23]
	v_cndmask_b32_e64 v18, v18, v37, s[20:21]
	v_cndmask_b32_e64 v18, v18, v39, s[18:19]
	v_cndmask_b32_e64 v18, v18, v41, s[16:17]
	v_cndmask_b32_e64 v18, v18, v43, s[14:15]
	v_cndmask_b32_e64 v18, v18, v45, s[12:13]
	v_cndmask_b32_e64 v18, v18, v47, s[10:11]
	v_cndmask_b32_e64 v18, v18, v49, s[8:9]
	v_cndmask_b32_e64 v18, v18, v22, s[6:7]
	v_mov_b32_e32 v19, v18
	s_nop 1
	v_permlane16_swap_b32 v19, v18
	v_add_f32_e32 v18, v18, v19
	v_mov_b32_e32 v19, v18
	s_nop 1
	v_permlane32_swap_b32 v19, v18
	v_add_f32_e32 v18, v18, v19
	s_and_saveexec_b64 s[2:3], s[4:5]
	s_cbranch_execz .LBB0_249
	v_mul_f32_e32 v19, v242, v34
	v_mul_f32_e32 v19, v214, v19
	v_fmac_f32_e32 v18, v215, v19
	v_mul_f32_e32 v19, 0x3d372713, v18
	v_mul_f32_e32 v19, v18, v19
	v_fma_f32 v19, v18, v19, v18
	v_mul_f32_e32 v19, 0xbfcc422a, v19
	v_mul_f32_e32 v19, 0x3fb8aa3b, v19
	v_exp_f32_e32 v19, v19
	s_ashr_i32 s71, s70, 31
	s_lshl_b64 s[56:57], s[70:71], 12
	v_add_f32_e32 v19, 1.0, v19
	v_rcp_f32_e32 v19, v19
	s_nop 0
	v_mul_f32_e32 v20, v18, v19
	v_lshl_add_u64 v[18:19], v[152:153], 0, s[56:57]
	global_store_dword v[18:19], v20, off
	s_branch .LBB0_249
